# phase 13 pooling: hand-written fast path for full-window prompt rows (16 rows x 256 cols per wave, all row loads up front, same add order, exact 1/WIN multiply); hipcc loop skips those rows
# speedup vs baseline: 1.0767x; 1.0379x over previous
; DI float bflo(unsigned u) { return __uint_as_float(u << 16); }
; DI float bfhi(unsigned u) { return __uint_as_float(u & 0xffff0000u); }
; template <int WIN>
; DI void pool_elem(const Params& p, int row, int c) {
;     ...
;   unsigned uu = *(const unsigned*)(P2 + (size_t)row * 2048 + c);
;   const float u0 = bflo(uu), u1 = bfhi(uu);
;   float s0 = u0, s1 = u1, cnt;
;   if (row < NPR) {
;     const int t = row & 2047, b = row >> 11;
;     if (t >= WIN - 1) {
;       cnt = (float)WIN;
;       unsigned w[WIN - 1];
; #pragma unroll
;       for (int j = 1; j < WIN; ++j) w[j - 1] = *(const unsigned*)(P2 + (size_t)(row - j) * 2048 + c);
; #pragma unroll
;       for (int j = 1; j < WIN; ++j) { s0 += bflo(w[j - 1]); s1 += bfhi(w[j - 1]); }
;     } else {
;       cnt = (float)(t + 1);
;       for (int j = 1; j <= t; ++j) {
;         unsigned w = *(const unsigned*)(P2 + (size_t)(row - j) * 2048 + c);
;         s0 += bflo(w); s1 += bfhi(w);
;       }
;     }
;     if (t >= 2033) {
;       float2 o = {u0, u1};
;       *(float2*)(p.out + O_POOLP + ((size_t)b * 15 + (t - 2033)) * 1024 + c) = o;
;     }
;   } else {
;     const int s = row - NPR;
;     cnt = (float)WIN;
;     const float* sp = p.state_pool + (size_t)s * 15 * 1024 + c;
;     float2 st[15];
; #pragma unroll
;     for (int j = 0; j < 15; ++j) st[j] = *(const float2*)(sp + (size_t)j * 1024);
; #pragma unroll
;     for (int j = 1; j < WIN; ++j) { s0 += st[15 - j].x; s1 += st[15 - j].y; }
;     float* op = p.out + O_POOLS + (size_t)s * 15 * 1024 + c;
; #pragma unroll
;     for (int j = 0; j < 14; ++j) *(float2*)(op + (size_t)j * 1024) = st[j + 1];
;     float2 o = {u0, u1};
;     *(float2*)(op + (size_t)14 * 1024) = o;
;   }
;   *(unsigned*)(p.MIX + (size_t)row * 1024 + c) = pack2(s0 / cnt - u0, s1 / cnt - u1);
.LBB0_1246:
	v_readlane_b32 s4, v254, 2
	v_readlane_b32 s5, v254, 3
	s_cmp_lt_i32 s4, 14
	s_cselect_b64 s[0:1], -1, 0
	s_cmp_gt_i32 s5, 12
	s_cselect_b64 s[2:3], -1, 0
	s_and_b64 s[0:1], s[0:1], s[2:3]
	s_andn2_b64 vcc, exec, s[0:1]
	v_mov_b32_e32 v1, s5
	v_mov_b32_e32 v0, s4
	v_lshl_add_u32 v198, s46, 8, v196
	s_cbranch_vccnz .LBB0_1314
	s_load_dwordx4 s[8:11], s[92:93], 0x150
	s_load_dwordx2 s[12:13], s[92:93], 0xf8
	v_lshrrev_b32_e32 v8, 6, v196
	v_and_b32_e32 v10, 63, v196
	v_readfirstlane_b32 s14, v8
	v_lshlrev_b32_e32 v11, 3, v10
	s_mov_b32 s15, s46
	s_lshl_b32 s16, s14, 9
	v_add_u32_e32 v11, s16, v11
	v_lshlrev_b32_e32 v12, 1, v11
	s_waitcnt lgkmcnt(0)
.Lp13f_loop:
	s_cmp_ge_u32 s15, 1016
	s_cbranch_scc1 .Lp13f_done
	s_mul_hi_u32 s17, s15, 0x2040811
	s_mul_i32 s18, s17, 127
	s_sub_u32 s18, s15, s18
	s_add_u32 s19, s18, 1
	s_lshl_b32 s19, s19, 4
	s_lshl_b32 s20, s17, 11
	s_add_u32 s20, s20, s19
	s_lshl_b32 s21, s20, 11
	s_add_u32 s24, s10, s21
	s_addc_u32 s25, s11, 0
	s_cmp_eq_u32 s14, 0
	s_cbranch_scc1 .Lp13f_w0
	s_cmp_eq_u32 s14, 1
	s_cbranch_scc1 .Lp13f_w1
	s_cmp_eq_u32 s14, 2
	s_cbranch_scc1 .Lp13f_w2
	s_branch .Lp13f_w3
.Lp13f_w0:
	s_sub_u32 s26, s20, 1
	s_lshl_b32 s27, s26, 12
	s_lshr_b32 s28, s26, 20
	s_add_u32 s22, s8, s27
	s_addc_u32 s23, s9, s28
	global_load_dwordx2 v[16:17], v11, s[22:23]
	s_add_u32 s22, s22, 0x1000
	s_addc_u32 s23, s23, 0
	global_load_dwordx2 v[20:21], v11, s[22:23]
	s_add_u32 s22, s22, 0x1000
	s_addc_u32 s23, s23, 0
	global_load_dwordx2 v[24:25], v11, s[22:23]
	s_add_u32 s22, s22, 0x1000
	s_addc_u32 s23, s23, 0
	global_load_dwordx2 v[28:29], v11, s[22:23]
	s_add_u32 s22, s22, 0x1000
	s_addc_u32 s23, s23, 0
	global_load_dwordx2 v[32:33], v11, s[22:23]
	s_add_u32 s22, s22, 0x1000
	s_addc_u32 s23, s23, 0
	global_load_dwordx2 v[36:37], v11, s[22:23]
	s_add_u32 s22, s22, 0x1000
	s_addc_u32 s23, s23, 0
	global_load_dwordx2 v[40:41], v11, s[22:23]
	s_add_u32 s22, s22, 0x1000
	s_addc_u32 s23, s23, 0
	global_load_dwordx2 v[44:45], v11, s[22:23]
	s_add_u32 s22, s22, 0x1000
	s_addc_u32 s23, s23, 0
	global_load_dwordx2 v[48:49], v11, s[22:23]
	s_add_u32 s22, s22, 0x1000
	s_addc_u32 s23, s23, 0
	global_load_dwordx2 v[52:53], v11, s[22:23]
	s_add_u32 s22, s22, 0x1000
	s_addc_u32 s23, s23, 0
	global_load_dwordx2 v[56:57], v11, s[22:23]
	s_add_u32 s22, s22, 0x1000
	s_addc_u32 s23, s23, 0
	global_load_dwordx2 v[60:61], v11, s[22:23]
	s_add_u32 s22, s22, 0x1000
	s_addc_u32 s23, s23, 0
	global_load_dwordx2 v[64:65], v11, s[22:23]
	s_add_u32 s22, s22, 0x1000
	s_addc_u32 s23, s23, 0
	global_load_dwordx2 v[68:69], v11, s[22:23]
	s_add_u32 s22, s22, 0x1000
	s_addc_u32 s23, s23, 0
	global_load_dwordx2 v[72:73], v11, s[22:23]
	s_add_u32 s22, s22, 0x1000
	s_addc_u32 s23, s23, 0
	global_load_dwordx2 v[76:77], v11, s[22:23]
	s_add_u32 s22, s22, 0x1000
	s_addc_u32 s23, s23, 0
	global_load_dwordx2 v[80:81], v11, s[22:23]
	s_add_u32 s22, s22, 0x1000
	s_addc_u32 s23, s23, 0
	s_waitcnt vmcnt(15)
	v_and_b32_e32 v19, 0xffff0000, v17
	v_lshlrev_b32_e32 v18, 16, v17
	v_and_b32_e32 v17, 0xffff0000, v16
	v_lshlrev_b32_e32 v16, 16, v16
	v_and_b32_e32 v23, 0xffff0000, v21
	v_lshlrev_b32_e32 v22, 16, v21
	v_and_b32_e32 v21, 0xffff0000, v20
	v_lshlrev_b32_e32 v20, 16, v20
	v_add_f32_e32 v140, v20, v16
	v_add_f32_e32 v141, v21, v17
	v_add_f32_e32 v142, v22, v18
	v_add_f32_e32 v143, v23, v19
	v_mul_f32_e32 v140, 0.5, v140
	v_mul_f32_e32 v141, 0.5, v141
	v_mul_f32_e32 v142, 0.5, v142
	v_mul_f32_e32 v143, 0.5, v143
	v_sub_f32_e32 v140, v140, v20
	v_sub_f32_e32 v141, v141, v21
	v_sub_f32_e32 v142, v142, v22
	v_sub_f32_e32 v143, v143, v23
	v_cvt_pk_bf16_f32 v144, v140, v141
	v_cvt_pk_bf16_f32 v145, v142, v143
	global_store_dwordx2 v11, v[144:145], s[24:25]
	s_add_u32 s24, s24, 0x800
	s_addc_u32 s25, s25, 0
	s_waitcnt vmcnt(14)
	v_and_b32_e32 v27, 0xffff0000, v25
	v_lshlrev_b32_e32 v26, 16, v25
	v_and_b32_e32 v25, 0xffff0000, v24
	v_lshlrev_b32_e32 v24, 16, v24
	v_add_f32_e32 v140, v24, v20
	v_add_f32_e32 v141, v25, v21
	v_add_f32_e32 v142, v26, v22
	v_add_f32_e32 v143, v27, v23
	v_mul_f32_e32 v140, 0.5, v140
	v_mul_f32_e32 v141, 0.5, v141
	v_mul_f32_e32 v142, 0.5, v142
	v_mul_f32_e32 v143, 0.5, v143
	v_sub_f32_e32 v140, v140, v24
	v_sub_f32_e32 v141, v141, v25
	v_sub_f32_e32 v142, v142, v26
	v_sub_f32_e32 v143, v143, v27
	v_cvt_pk_bf16_f32 v144, v140, v141
	v_cvt_pk_bf16_f32 v145, v142, v143
	global_store_dwordx2 v11, v[144:145], s[24:25]
	s_add_u32 s24, s24, 0x800
	s_addc_u32 s25, s25, 0
	s_waitcnt vmcnt(13)
	v_and_b32_e32 v31, 0xffff0000, v29
	v_lshlrev_b32_e32 v30, 16, v29
	v_and_b32_e32 v29, 0xffff0000, v28
	v_lshlrev_b32_e32 v28, 16, v28
	v_add_f32_e32 v140, v28, v24
	v_add_f32_e32 v141, v29, v25
	v_add_f32_e32 v142, v30, v26
	v_add_f32_e32 v143, v31, v27
	v_mul_f32_e32 v140, 0.5, v140
	v_mul_f32_e32 v141, 0.5, v141
	v_mul_f32_e32 v142, 0.5, v142
	v_mul_f32_e32 v143, 0.5, v143
	v_sub_f32_e32 v140, v140, v28
	v_sub_f32_e32 v141, v141, v29
	v_sub_f32_e32 v142, v142, v30
	v_sub_f32_e32 v143, v143, v31
	v_cvt_pk_bf16_f32 v144, v140, v141
	v_cvt_pk_bf16_f32 v145, v142, v143
	global_store_dwordx2 v11, v[144:145], s[24:25]
	s_add_u32 s24, s24, 0x800
	s_addc_u32 s25, s25, 0
	s_waitcnt vmcnt(12)
	v_and_b32_e32 v35, 0xffff0000, v33
	v_lshlrev_b32_e32 v34, 16, v33
	v_and_b32_e32 v33, 0xffff0000, v32
	v_lshlrev_b32_e32 v32, 16, v32
	v_add_f32_e32 v140, v32, v28
	v_add_f32_e32 v141, v33, v29
	v_add_f32_e32 v142, v34, v30
	v_add_f32_e32 v143, v35, v31
	v_mul_f32_e32 v140, 0.5, v140
	v_mul_f32_e32 v141, 0.5, v141
	v_mul_f32_e32 v142, 0.5, v142
	v_mul_f32_e32 v143, 0.5, v143
	v_sub_f32_e32 v140, v140, v32
	v_sub_f32_e32 v141, v141, v33
	v_sub_f32_e32 v142, v142, v34
	v_sub_f32_e32 v143, v143, v35
	v_cvt_pk_bf16_f32 v144, v140, v141
	v_cvt_pk_bf16_f32 v145, v142, v143
	global_store_dwordx2 v11, v[144:145], s[24:25]
	s_add_u32 s24, s24, 0x800
	s_addc_u32 s25, s25, 0
	s_waitcnt vmcnt(11)
; DI float bflo(unsigned u) { return __uint_as_float(u << 16); }
; DI float bfhi(unsigned u) { return __uint_as_float(u & 0xffff0000u); }
; template <int WIN>
; DI void pool_elem(const Params& p, int row, int c) {
;     ...
;     if (t >= WIN - 1) {
;       cnt = (float)WIN;
;       unsigned w[WIN - 1];
; #pragma unroll
;       for (int j = 1; j < WIN; ++j) w[j - 1] = *(const unsigned*)(P2 + (size_t)(row - j) * 2048 + c);
; #pragma unroll
;       for (int j = 1; j < WIN; ++j) { s0 += bflo(w[j - 1]); s1 += bfhi(w[j - 1]); }
;     ...
;   *(unsigned*)(p.MIX + (size_t)row * 1024 + c) = pack2(s0 / cnt - u0, s1 / cnt - u1);
	v_and_b32_e32 v39, 0xffff0000, v37
	v_lshlrev_b32_e32 v38, 16, v37
	v_and_b32_e32 v37, 0xffff0000, v36
	v_lshlrev_b32_e32 v36, 16, v36
	v_add_f32_e32 v140, v36, v32
	v_add_f32_e32 v141, v37, v33
	v_add_f32_e32 v142, v38, v34
	v_add_f32_e32 v143, v39, v35
	v_mul_f32_e32 v140, 0.5, v140
	v_mul_f32_e32 v141, 0.5, v141
	v_mul_f32_e32 v142, 0.5, v142
	v_mul_f32_e32 v143, 0.5, v143
	v_sub_f32_e32 v140, v140, v36
	v_sub_f32_e32 v141, v141, v37
	v_sub_f32_e32 v142, v142, v38
	v_sub_f32_e32 v143, v143, v39
	v_cvt_pk_bf16_f32 v144, v140, v141
	v_cvt_pk_bf16_f32 v145, v142, v143
	global_store_dwordx2 v11, v[144:145], s[24:25]
	s_add_u32 s24, s24, 0x800
	s_addc_u32 s25, s25, 0
	s_waitcnt vmcnt(10)
	v_and_b32_e32 v43, 0xffff0000, v41
	v_lshlrev_b32_e32 v42, 16, v41
	v_and_b32_e32 v41, 0xffff0000, v40
	v_lshlrev_b32_e32 v40, 16, v40
	v_add_f32_e32 v140, v40, v36
	v_add_f32_e32 v141, v41, v37
	v_add_f32_e32 v142, v42, v38
	v_add_f32_e32 v143, v43, v39
	v_mul_f32_e32 v140, 0.5, v140
	v_mul_f32_e32 v141, 0.5, v141
	v_mul_f32_e32 v142, 0.5, v142
	v_mul_f32_e32 v143, 0.5, v143
	v_sub_f32_e32 v140, v140, v40
	v_sub_f32_e32 v141, v141, v41
	v_sub_f32_e32 v142, v142, v42
	v_sub_f32_e32 v143, v143, v43
	v_cvt_pk_bf16_f32 v144, v140, v141
	v_cvt_pk_bf16_f32 v145, v142, v143
	global_store_dwordx2 v11, v[144:145], s[24:25]
	s_add_u32 s24, s24, 0x800
	s_addc_u32 s25, s25, 0
	s_waitcnt vmcnt(9)
	v_and_b32_e32 v47, 0xffff0000, v45
	v_lshlrev_b32_e32 v46, 16, v45
	v_and_b32_e32 v45, 0xffff0000, v44
	v_lshlrev_b32_e32 v44, 16, v44
	v_add_f32_e32 v140, v44, v40
	v_add_f32_e32 v141, v45, v41
	v_add_f32_e32 v142, v46, v42
	v_add_f32_e32 v143, v47, v43
	v_mul_f32_e32 v140, 0.5, v140
	v_mul_f32_e32 v141, 0.5, v141
	v_mul_f32_e32 v142, 0.5, v142
	v_mul_f32_e32 v143, 0.5, v143
	v_sub_f32_e32 v140, v140, v44
	v_sub_f32_e32 v141, v141, v45
	v_sub_f32_e32 v142, v142, v46
	v_sub_f32_e32 v143, v143, v47
	v_cvt_pk_bf16_f32 v144, v140, v141
	v_cvt_pk_bf16_f32 v145, v142, v143
	global_store_dwordx2 v11, v[144:145], s[24:25]
	s_add_u32 s24, s24, 0x800
	s_addc_u32 s25, s25, 0
	s_waitcnt vmcnt(8)
	v_and_b32_e32 v51, 0xffff0000, v49
	v_lshlrev_b32_e32 v50, 16, v49
	v_and_b32_e32 v49, 0xffff0000, v48
	v_lshlrev_b32_e32 v48, 16, v48
	v_add_f32_e32 v140, v48, v44
	v_add_f32_e32 v141, v49, v45
	v_add_f32_e32 v142, v50, v46
	v_add_f32_e32 v143, v51, v47
	v_mul_f32_e32 v140, 0.5, v140
	v_mul_f32_e32 v141, 0.5, v141
	v_mul_f32_e32 v142, 0.5, v142
	v_mul_f32_e32 v143, 0.5, v143
	v_sub_f32_e32 v140, v140, v48
	v_sub_f32_e32 v141, v141, v49
	v_sub_f32_e32 v142, v142, v50
	v_sub_f32_e32 v143, v143, v51
	v_cvt_pk_bf16_f32 v144, v140, v141
	v_cvt_pk_bf16_f32 v145, v142, v143
	global_store_dwordx2 v11, v[144:145], s[24:25]
	s_add_u32 s24, s24, 0x800
	s_addc_u32 s25, s25, 0
	s_waitcnt vmcnt(7)
	v_and_b32_e32 v55, 0xffff0000, v53
	v_lshlrev_b32_e32 v54, 16, v53
	v_and_b32_e32 v53, 0xffff0000, v52
	v_lshlrev_b32_e32 v52, 16, v52
	v_add_f32_e32 v140, v52, v48
	v_add_f32_e32 v141, v53, v49
	v_add_f32_e32 v142, v54, v50
	v_add_f32_e32 v143, v55, v51
	v_mul_f32_e32 v140, 0.5, v140
	v_mul_f32_e32 v141, 0.5, v141
	v_mul_f32_e32 v142, 0.5, v142
	v_mul_f32_e32 v143, 0.5, v143
	v_sub_f32_e32 v140, v140, v52
	v_sub_f32_e32 v141, v141, v53
	v_sub_f32_e32 v142, v142, v54
	v_sub_f32_e32 v143, v143, v55
	v_cvt_pk_bf16_f32 v144, v140, v141
	v_cvt_pk_bf16_f32 v145, v142, v143
	global_store_dwordx2 v11, v[144:145], s[24:25]
	s_add_u32 s24, s24, 0x800
	s_addc_u32 s25, s25, 0
	s_waitcnt vmcnt(6)
	v_and_b32_e32 v59, 0xffff0000, v57
	v_lshlrev_b32_e32 v58, 16, v57
	v_and_b32_e32 v57, 0xffff0000, v56
	v_lshlrev_b32_e32 v56, 16, v56
	v_add_f32_e32 v140, v56, v52
	v_add_f32_e32 v141, v57, v53
	v_add_f32_e32 v142, v58, v54
	v_add_f32_e32 v143, v59, v55
	v_mul_f32_e32 v140, 0.5, v140
	v_mul_f32_e32 v141, 0.5, v141
	v_mul_f32_e32 v142, 0.5, v142
	v_mul_f32_e32 v143, 0.5, v143
	v_sub_f32_e32 v140, v140, v56
	v_sub_f32_e32 v141, v141, v57
	v_sub_f32_e32 v142, v142, v58
	v_sub_f32_e32 v143, v143, v59
	v_cvt_pk_bf16_f32 v144, v140, v141
	v_cvt_pk_bf16_f32 v145, v142, v143
	global_store_dwordx2 v11, v[144:145], s[24:25]
	s_add_u32 s24, s24, 0x800
	s_addc_u32 s25, s25, 0
	s_waitcnt vmcnt(5)
	v_and_b32_e32 v63, 0xffff0000, v61
	v_lshlrev_b32_e32 v62, 16, v61
	v_and_b32_e32 v61, 0xffff0000, v60
	v_lshlrev_b32_e32 v60, 16, v60
	v_add_f32_e32 v140, v60, v56
	v_add_f32_e32 v141, v61, v57
	v_add_f32_e32 v142, v62, v58
	v_add_f32_e32 v143, v63, v59
	v_mul_f32_e32 v140, 0.5, v140
	v_mul_f32_e32 v141, 0.5, v141
	v_mul_f32_e32 v142, 0.5, v142
	v_mul_f32_e32 v143, 0.5, v143
	v_sub_f32_e32 v140, v140, v60
	v_sub_f32_e32 v141, v141, v61
	v_sub_f32_e32 v142, v142, v62
	v_sub_f32_e32 v143, v143, v63
	v_cvt_pk_bf16_f32 v144, v140, v141
	v_cvt_pk_bf16_f32 v145, v142, v143
	global_store_dwordx2 v11, v[144:145], s[24:25]
	s_add_u32 s24, s24, 0x800
	s_addc_u32 s25, s25, 0
	s_waitcnt vmcnt(4)
	v_and_b32_e32 v67, 0xffff0000, v65
	v_lshlrev_b32_e32 v66, 16, v65
	v_and_b32_e32 v65, 0xffff0000, v64
	v_lshlrev_b32_e32 v64, 16, v64
	v_add_f32_e32 v140, v64, v60
	v_add_f32_e32 v141, v65, v61
	v_add_f32_e32 v142, v66, v62
	v_add_f32_e32 v143, v67, v63
	v_mul_f32_e32 v140, 0.5, v140
	v_mul_f32_e32 v141, 0.5, v141
	v_mul_f32_e32 v142, 0.5, v142
	v_mul_f32_e32 v143, 0.5, v143
	v_sub_f32_e32 v140, v140, v64
	v_sub_f32_e32 v141, v141, v65
	v_sub_f32_e32 v142, v142, v66
	v_sub_f32_e32 v143, v143, v67
	v_cvt_pk_bf16_f32 v144, v140, v141
	v_cvt_pk_bf16_f32 v145, v142, v143
	global_store_dwordx2 v11, v[144:145], s[24:25]
	s_add_u32 s24, s24, 0x800
	s_addc_u32 s25, s25, 0
	s_waitcnt vmcnt(3)
; DI float bflo(unsigned u) { return __uint_as_float(u << 16); }
; DI float bfhi(unsigned u) { return __uint_as_float(u & 0xffff0000u); }
; template <int WIN>
; DI void pool_elem(const Params& p, int row, int c) {
;     ...
;     if (t >= WIN - 1) {
;       cnt = (float)WIN;
;       unsigned w[WIN - 1];
; #pragma unroll
;       for (int j = 1; j < WIN; ++j) w[j - 1] = *(const unsigned*)(P2 + (size_t)(row - j) * 2048 + c);
; #pragma unroll
;       for (int j = 1; j < WIN; ++j) { s0 += bflo(w[j - 1]); s1 += bfhi(w[j - 1]); }
;     } else {
;       cnt = (float)(t + 1);
;       for (int j = 1; j <= t; ++j) {
;         unsigned w = *(const unsigned*)(P2 + (size_t)(row - j) * 2048 + c);
;         s0 += bflo(w); s1 += bfhi(w);
;       }
;     }
;     if (t >= 2033) {
;       float2 o = {u0, u1};
;       *(float2*)(p.out + O_POOLP + ((size_t)b * 15 + (t - 2033)) * 1024 + c) = o;
;     }
;     ...
;   *(unsigned*)(p.MIX + (size_t)row * 1024 + c) = pack2(s0 / cnt - u0, s1 / cnt - u1);
	v_and_b32_e32 v71, 0xffff0000, v69
	v_lshlrev_b32_e32 v70, 16, v69
	v_and_b32_e32 v69, 0xffff0000, v68
	v_lshlrev_b32_e32 v68, 16, v68
	v_add_f32_e32 v140, v68, v64
	v_add_f32_e32 v141, v69, v65
	v_add_f32_e32 v142, v70, v66
	v_add_f32_e32 v143, v71, v67
	v_mul_f32_e32 v140, 0.5, v140
	v_mul_f32_e32 v141, 0.5, v141
	v_mul_f32_e32 v142, 0.5, v142
	v_mul_f32_e32 v143, 0.5, v143
	v_sub_f32_e32 v140, v140, v68
	v_sub_f32_e32 v141, v141, v69
	v_sub_f32_e32 v142, v142, v70
	v_sub_f32_e32 v143, v143, v71
	v_cvt_pk_bf16_f32 v144, v140, v141
	v_cvt_pk_bf16_f32 v145, v142, v143
	global_store_dwordx2 v11, v[144:145], s[24:25]
	s_add_u32 s24, s24, 0x800
	s_addc_u32 s25, s25, 0
	s_waitcnt vmcnt(2)
	v_and_b32_e32 v75, 0xffff0000, v73
	v_lshlrev_b32_e32 v74, 16, v73
	v_and_b32_e32 v73, 0xffff0000, v72
	v_lshlrev_b32_e32 v72, 16, v72
	v_add_f32_e32 v140, v72, v68
	v_add_f32_e32 v141, v73, v69
	v_add_f32_e32 v142, v74, v70
	v_add_f32_e32 v143, v75, v71
	v_mul_f32_e32 v140, 0.5, v140
	v_mul_f32_e32 v141, 0.5, v141
	v_mul_f32_e32 v142, 0.5, v142
	v_mul_f32_e32 v143, 0.5, v143
	v_sub_f32_e32 v140, v140, v72
	v_sub_f32_e32 v141, v141, v73
	v_sub_f32_e32 v142, v142, v74
	v_sub_f32_e32 v143, v143, v75
	v_cvt_pk_bf16_f32 v144, v140, v141
	v_cvt_pk_bf16_f32 v145, v142, v143
	global_store_dwordx2 v11, v[144:145], s[24:25]
	s_add_u32 s24, s24, 0x800
	s_addc_u32 s25, s25, 0
	s_waitcnt vmcnt(1)
	v_and_b32_e32 v79, 0xffff0000, v77
	v_lshlrev_b32_e32 v78, 16, v77
	v_and_b32_e32 v77, 0xffff0000, v76
	v_lshlrev_b32_e32 v76, 16, v76
	v_add_f32_e32 v140, v76, v72
	v_add_f32_e32 v141, v77, v73
	v_add_f32_e32 v142, v78, v74
	v_add_f32_e32 v143, v79, v75
	v_mul_f32_e32 v140, 0.5, v140
	v_mul_f32_e32 v141, 0.5, v141
	v_mul_f32_e32 v142, 0.5, v142
	v_mul_f32_e32 v143, 0.5, v143
	v_sub_f32_e32 v140, v140, v76
	v_sub_f32_e32 v141, v141, v77
	v_sub_f32_e32 v142, v142, v78
	v_sub_f32_e32 v143, v143, v79
	v_cvt_pk_bf16_f32 v144, v140, v141
	v_cvt_pk_bf16_f32 v145, v142, v143
	global_store_dwordx2 v11, v[144:145], s[24:25]
	s_add_u32 s24, s24, 0x800
	s_addc_u32 s25, s25, 0
	s_waitcnt vmcnt(0)
	v_and_b32_e32 v83, 0xffff0000, v81
	v_lshlrev_b32_e32 v82, 16, v81
	v_and_b32_e32 v81, 0xffff0000, v80
	v_lshlrev_b32_e32 v80, 16, v80
	v_add_f32_e32 v140, v80, v76
	v_add_f32_e32 v141, v81, v77
	v_add_f32_e32 v142, v82, v78
	v_add_f32_e32 v143, v83, v79
	v_mul_f32_e32 v140, 0.5, v140
	v_mul_f32_e32 v141, 0.5, v141
	v_mul_f32_e32 v142, 0.5, v142
	v_mul_f32_e32 v143, 0.5, v143
	v_sub_f32_e32 v140, v140, v80
	v_sub_f32_e32 v141, v141, v81
	v_sub_f32_e32 v142, v142, v82
	v_sub_f32_e32 v143, v143, v83
	v_cvt_pk_bf16_f32 v144, v140, v141
	v_cvt_pk_bf16_f32 v145, v142, v143
	global_store_dwordx2 v11, v[144:145], s[24:25]
	s_add_u32 s24, s24, 0x800
	s_addc_u32 s25, s25, 0
	s_cmp_eq_u32 s18, 126
	s_cbranch_scc0 .Lp13f_next0
	s_mul_i32 s26, s17, 61440
	s_add_u32 s26, s26, 0x431c000
	s_add_u32 s22, s12, s26
	s_addc_u32 s23, s13, 0
	global_store_dwordx4 v12, v[24:27], s[22:23]
	s_add_u32 s22, s22, 0x1000
	s_addc_u32 s23, s23, 0
	global_store_dwordx4 v12, v[28:31], s[22:23]
	s_add_u32 s22, s22, 0x1000
	s_addc_u32 s23, s23, 0
	global_store_dwordx4 v12, v[32:35], s[22:23]
	s_add_u32 s22, s22, 0x1000
	s_addc_u32 s23, s23, 0
	global_store_dwordx4 v12, v[36:39], s[22:23]
	s_add_u32 s22, s22, 0x1000
	s_addc_u32 s23, s23, 0
	global_store_dwordx4 v12, v[40:43], s[22:23]
	s_add_u32 s22, s22, 0x1000
	s_addc_u32 s23, s23, 0
	global_store_dwordx4 v12, v[44:47], s[22:23]
	s_add_u32 s22, s22, 0x1000
	s_addc_u32 s23, s23, 0
	global_store_dwordx4 v12, v[48:51], s[22:23]
	s_add_u32 s22, s22, 0x1000
	s_addc_u32 s23, s23, 0
	global_store_dwordx4 v12, v[52:55], s[22:23]
	s_add_u32 s22, s22, 0x1000
	s_addc_u32 s23, s23, 0
	global_store_dwordx4 v12, v[56:59], s[22:23]
	s_add_u32 s22, s22, 0x1000
	s_addc_u32 s23, s23, 0
	global_store_dwordx4 v12, v[60:63], s[22:23]
	s_add_u32 s22, s22, 0x1000
	s_addc_u32 s23, s23, 0
	global_store_dwordx4 v12, v[64:67], s[22:23]
	s_add_u32 s22, s22, 0x1000
	s_addc_u32 s23, s23, 0
	global_store_dwordx4 v12, v[68:71], s[22:23]
	s_add_u32 s22, s22, 0x1000
	s_addc_u32 s23, s23, 0
	global_store_dwordx4 v12, v[72:75], s[22:23]
	s_add_u32 s22, s22, 0x1000
	s_addc_u32 s23, s23, 0
	global_store_dwordx4 v12, v[76:79], s[22:23]
	s_add_u32 s22, s22, 0x1000
	s_addc_u32 s23, s23, 0
	global_store_dwordx4 v12, v[80:83], s[22:23]
	s_add_u32 s22, s22, 0x1000
	s_addc_u32 s23, s23, 0
.Lp13f_next0:
	s_branch .Lp13f_next
; DI float bflo(unsigned u) { return __uint_as_float(u << 16); }
; DI float bfhi(unsigned u) { return __uint_as_float(u & 0xffff0000u); }
; template <int WIN>
; DI void pool_elem(const Params& p, int row, int c) {
;     ...
;     if (t >= WIN - 1) {
;       cnt = (float)WIN;
;       unsigned w[WIN - 1];
; #pragma unroll
;       for (int j = 1; j < WIN; ++j) w[j - 1] = *(const unsigned*)(P2 + (size_t)(row - j) * 2048 + c);
; #pragma unroll
;       for (int j = 1; j < WIN; ++j) { s0 += bflo(w[j - 1]); s1 += bfhi(w[j - 1]); }
;     ...
;   *(unsigned*)(p.MIX + (size_t)row * 1024 + c) = pack2(s0 / cnt - u0, s1 / cnt - u1);
.Lp13f_w1:
	s_sub_u32 s26, s20, 3
	s_lshl_b32 s27, s26, 12
	s_lshr_b32 s28, s26, 20
	s_add_u32 s22, s8, s27
	s_addc_u32 s23, s9, s28
	global_load_dwordx2 v[16:17], v11, s[22:23]
	s_add_u32 s22, s22, 0x1000
	s_addc_u32 s23, s23, 0
	global_load_dwordx2 v[20:21], v11, s[22:23]
	s_add_u32 s22, s22, 0x1000
	s_addc_u32 s23, s23, 0
	global_load_dwordx2 v[24:25], v11, s[22:23]
	s_add_u32 s22, s22, 0x1000
	s_addc_u32 s23, s23, 0
	global_load_dwordx2 v[28:29], v11, s[22:23]
	s_add_u32 s22, s22, 0x1000
	s_addc_u32 s23, s23, 0
	global_load_dwordx2 v[32:33], v11, s[22:23]
	s_add_u32 s22, s22, 0x1000
	s_addc_u32 s23, s23, 0
	global_load_dwordx2 v[36:37], v11, s[22:23]
	s_add_u32 s22, s22, 0x1000
	s_addc_u32 s23, s23, 0
	global_load_dwordx2 v[40:41], v11, s[22:23]
	s_add_u32 s22, s22, 0x1000
	s_addc_u32 s23, s23, 0
	global_load_dwordx2 v[44:45], v11, s[22:23]
	s_add_u32 s22, s22, 0x1000
	s_addc_u32 s23, s23, 0
	global_load_dwordx2 v[48:49], v11, s[22:23]
	s_add_u32 s22, s22, 0x1000
	s_addc_u32 s23, s23, 0
	global_load_dwordx2 v[52:53], v11, s[22:23]
	s_add_u32 s22, s22, 0x1000
	s_addc_u32 s23, s23, 0
	global_load_dwordx2 v[56:57], v11, s[22:23]
	s_add_u32 s22, s22, 0x1000
	s_addc_u32 s23, s23, 0
	global_load_dwordx2 v[60:61], v11, s[22:23]
	s_add_u32 s22, s22, 0x1000
	s_addc_u32 s23, s23, 0
	global_load_dwordx2 v[64:65], v11, s[22:23]
	s_add_u32 s22, s22, 0x1000
	s_addc_u32 s23, s23, 0
	global_load_dwordx2 v[68:69], v11, s[22:23]
	s_add_u32 s22, s22, 0x1000
	s_addc_u32 s23, s23, 0
	global_load_dwordx2 v[72:73], v11, s[22:23]
	s_add_u32 s22, s22, 0x1000
	s_addc_u32 s23, s23, 0
	global_load_dwordx2 v[76:77], v11, s[22:23]
	s_add_u32 s22, s22, 0x1000
	s_addc_u32 s23, s23, 0
	global_load_dwordx2 v[80:81], v11, s[22:23]
	s_add_u32 s22, s22, 0x1000
	s_addc_u32 s23, s23, 0
	global_load_dwordx2 v[84:85], v11, s[22:23]
	s_add_u32 s22, s22, 0x1000
	s_addc_u32 s23, s23, 0
	global_load_dwordx2 v[88:89], v11, s[22:23]
	s_add_u32 s22, s22, 0x1000
	s_addc_u32 s23, s23, 0
	s_waitcnt vmcnt(15)
	v_and_b32_e32 v19, 0xffff0000, v17
	v_lshlrev_b32_e32 v18, 16, v17
	v_and_b32_e32 v17, 0xffff0000, v16
	v_lshlrev_b32_e32 v16, 16, v16
	v_and_b32_e32 v23, 0xffff0000, v21
	v_lshlrev_b32_e32 v22, 16, v21
	v_and_b32_e32 v21, 0xffff0000, v20
	v_lshlrev_b32_e32 v20, 16, v20
	v_and_b32_e32 v27, 0xffff0000, v25
	v_lshlrev_b32_e32 v26, 16, v25
	v_and_b32_e32 v25, 0xffff0000, v24
	v_lshlrev_b32_e32 v24, 16, v24
	v_and_b32_e32 v31, 0xffff0000, v29
	v_lshlrev_b32_e32 v30, 16, v29
	v_and_b32_e32 v29, 0xffff0000, v28
	v_lshlrev_b32_e32 v28, 16, v28
	v_add_f32_e32 v140, v28, v24
	v_add_f32_e32 v141, v29, v25
	v_add_f32_e32 v142, v30, v26
	v_add_f32_e32 v143, v31, v27
	v_add_f32_e32 v140, v140, v20
	v_add_f32_e32 v141, v141, v21
	v_add_f32_e32 v142, v142, v22
	v_add_f32_e32 v143, v143, v23
	v_add_f32_e32 v140, v140, v16
	v_add_f32_e32 v141, v141, v17
	v_add_f32_e32 v142, v142, v18
	v_add_f32_e32 v143, v143, v19
	v_mul_f32_e32 v140, 0x3e800000, v140
	v_mul_f32_e32 v141, 0x3e800000, v141
	v_mul_f32_e32 v142, 0x3e800000, v142
	v_mul_f32_e32 v143, 0x3e800000, v143
	v_sub_f32_e32 v140, v140, v28
	v_sub_f32_e32 v141, v141, v29
	v_sub_f32_e32 v142, v142, v30
	v_sub_f32_e32 v143, v143, v31
	v_cvt_pk_bf16_f32 v144, v140, v141
	v_cvt_pk_bf16_f32 v145, v142, v143
	global_store_dwordx2 v11, v[144:145], s[24:25]
	s_add_u32 s24, s24, 0x800
	s_addc_u32 s25, s25, 0
	s_waitcnt vmcnt(14)
	v_and_b32_e32 v35, 0xffff0000, v33
	v_lshlrev_b32_e32 v34, 16, v33
	v_and_b32_e32 v33, 0xffff0000, v32
	v_lshlrev_b32_e32 v32, 16, v32
	v_add_f32_e32 v140, v32, v28
	v_add_f32_e32 v141, v33, v29
	v_add_f32_e32 v142, v34, v30
	v_add_f32_e32 v143, v35, v31
	v_add_f32_e32 v140, v140, v24
	v_add_f32_e32 v141, v141, v25
	v_add_f32_e32 v142, v142, v26
	v_add_f32_e32 v143, v143, v27
	v_add_f32_e32 v140, v140, v20
	v_add_f32_e32 v141, v141, v21
	v_add_f32_e32 v142, v142, v22
	v_add_f32_e32 v143, v143, v23
	v_mul_f32_e32 v140, 0x3e800000, v140
	v_mul_f32_e32 v141, 0x3e800000, v141
	v_mul_f32_e32 v142, 0x3e800000, v142
	v_mul_f32_e32 v143, 0x3e800000, v143
	v_sub_f32_e32 v140, v140, v32
	v_sub_f32_e32 v141, v141, v33
	v_sub_f32_e32 v142, v142, v34
	v_sub_f32_e32 v143, v143, v35
	v_cvt_pk_bf16_f32 v144, v140, v141
	v_cvt_pk_bf16_f32 v145, v142, v143
	global_store_dwordx2 v11, v[144:145], s[24:25]
	s_add_u32 s24, s24, 0x800
	s_addc_u32 s25, s25, 0
	s_waitcnt vmcnt(13)
	v_and_b32_e32 v39, 0xffff0000, v37
	v_lshlrev_b32_e32 v38, 16, v37
	v_and_b32_e32 v37, 0xffff0000, v36
	v_lshlrev_b32_e32 v36, 16, v36
	v_add_f32_e32 v140, v36, v32
	v_add_f32_e32 v141, v37, v33
	v_add_f32_e32 v142, v38, v34
	v_add_f32_e32 v143, v39, v35
	v_add_f32_e32 v140, v140, v28
	v_add_f32_e32 v141, v141, v29
	v_add_f32_e32 v142, v142, v30
	v_add_f32_e32 v143, v143, v31
	v_add_f32_e32 v140, v140, v24
	v_add_f32_e32 v141, v141, v25
	v_add_f32_e32 v142, v142, v26
	v_add_f32_e32 v143, v143, v27
	v_mul_f32_e32 v140, 0x3e800000, v140
	v_mul_f32_e32 v141, 0x3e800000, v141
	v_mul_f32_e32 v142, 0x3e800000, v142
	v_mul_f32_e32 v143, 0x3e800000, v143
	v_sub_f32_e32 v140, v140, v36
	v_sub_f32_e32 v141, v141, v37
	v_sub_f32_e32 v142, v142, v38
	v_sub_f32_e32 v143, v143, v39
	v_cvt_pk_bf16_f32 v144, v140, v141
	v_cvt_pk_bf16_f32 v145, v142, v143
	global_store_dwordx2 v11, v[144:145], s[24:25]
	s_add_u32 s24, s24, 0x800
	s_addc_u32 s25, s25, 0
	s_waitcnt vmcnt(12)
; DI float bflo(unsigned u) { return __uint_as_float(u << 16); }
; DI float bfhi(unsigned u) { return __uint_as_float(u & 0xffff0000u); }
; template <int WIN>
; DI void pool_elem(const Params& p, int row, int c) {
;     ...
;     if (t >= WIN - 1) {
;       cnt = (float)WIN;
;       unsigned w[WIN - 1];
; #pragma unroll
;       for (int j = 1; j < WIN; ++j) w[j - 1] = *(const unsigned*)(P2 + (size_t)(row - j) * 2048 + c);
; #pragma unroll
;       for (int j = 1; j < WIN; ++j) { s0 += bflo(w[j - 1]); s1 += bfhi(w[j - 1]); }
;     ...
;   *(unsigned*)(p.MIX + (size_t)row * 1024 + c) = pack2(s0 / cnt - u0, s1 / cnt - u1);
	v_and_b32_e32 v43, 0xffff0000, v41
	v_lshlrev_b32_e32 v42, 16, v41
	v_and_b32_e32 v41, 0xffff0000, v40
	v_lshlrev_b32_e32 v40, 16, v40
	v_add_f32_e32 v140, v40, v36
	v_add_f32_e32 v141, v41, v37
	v_add_f32_e32 v142, v42, v38
	v_add_f32_e32 v143, v43, v39
	v_add_f32_e32 v140, v140, v32
	v_add_f32_e32 v141, v141, v33
	v_add_f32_e32 v142, v142, v34
	v_add_f32_e32 v143, v143, v35
	v_add_f32_e32 v140, v140, v28
	v_add_f32_e32 v141, v141, v29
	v_add_f32_e32 v142, v142, v30
	v_add_f32_e32 v143, v143, v31
	v_mul_f32_e32 v140, 0x3e800000, v140
	v_mul_f32_e32 v141, 0x3e800000, v141
	v_mul_f32_e32 v142, 0x3e800000, v142
	v_mul_f32_e32 v143, 0x3e800000, v143
	v_sub_f32_e32 v140, v140, v40
	v_sub_f32_e32 v141, v141, v41
	v_sub_f32_e32 v142, v142, v42
	v_sub_f32_e32 v143, v143, v43
	v_cvt_pk_bf16_f32 v144, v140, v141
	v_cvt_pk_bf16_f32 v145, v142, v143
	global_store_dwordx2 v11, v[144:145], s[24:25]
	s_add_u32 s24, s24, 0x800
	s_addc_u32 s25, s25, 0
	s_waitcnt vmcnt(11)
	v_and_b32_e32 v47, 0xffff0000, v45
	v_lshlrev_b32_e32 v46, 16, v45
	v_and_b32_e32 v45, 0xffff0000, v44
	v_lshlrev_b32_e32 v44, 16, v44
	v_add_f32_e32 v140, v44, v40
	v_add_f32_e32 v141, v45, v41
	v_add_f32_e32 v142, v46, v42
	v_add_f32_e32 v143, v47, v43
	v_add_f32_e32 v140, v140, v36
	v_add_f32_e32 v141, v141, v37
	v_add_f32_e32 v142, v142, v38
	v_add_f32_e32 v143, v143, v39
	v_add_f32_e32 v140, v140, v32
	v_add_f32_e32 v141, v141, v33
	v_add_f32_e32 v142, v142, v34
	v_add_f32_e32 v143, v143, v35
	v_mul_f32_e32 v140, 0x3e800000, v140
	v_mul_f32_e32 v141, 0x3e800000, v141
	v_mul_f32_e32 v142, 0x3e800000, v142
	v_mul_f32_e32 v143, 0x3e800000, v143
	v_sub_f32_e32 v140, v140, v44
	v_sub_f32_e32 v141, v141, v45
	v_sub_f32_e32 v142, v142, v46
	v_sub_f32_e32 v143, v143, v47
	v_cvt_pk_bf16_f32 v144, v140, v141
	v_cvt_pk_bf16_f32 v145, v142, v143
	global_store_dwordx2 v11, v[144:145], s[24:25]
	s_add_u32 s24, s24, 0x800
	s_addc_u32 s25, s25, 0
	s_waitcnt vmcnt(10)
	v_and_b32_e32 v51, 0xffff0000, v49
	v_lshlrev_b32_e32 v50, 16, v49
	v_and_b32_e32 v49, 0xffff0000, v48
	v_lshlrev_b32_e32 v48, 16, v48
	v_add_f32_e32 v140, v48, v44
	v_add_f32_e32 v141, v49, v45
	v_add_f32_e32 v142, v50, v46
	v_add_f32_e32 v143, v51, v47
	v_add_f32_e32 v140, v140, v40
	v_add_f32_e32 v141, v141, v41
	v_add_f32_e32 v142, v142, v42
	v_add_f32_e32 v143, v143, v43
	v_add_f32_e32 v140, v140, v36
	v_add_f32_e32 v141, v141, v37
	v_add_f32_e32 v142, v142, v38
	v_add_f32_e32 v143, v143, v39
	v_mul_f32_e32 v140, 0x3e800000, v140
	v_mul_f32_e32 v141, 0x3e800000, v141
	v_mul_f32_e32 v142, 0x3e800000, v142
	v_mul_f32_e32 v143, 0x3e800000, v143
	v_sub_f32_e32 v140, v140, v48
	v_sub_f32_e32 v141, v141, v49
	v_sub_f32_e32 v142, v142, v50
	v_sub_f32_e32 v143, v143, v51
	v_cvt_pk_bf16_f32 v144, v140, v141
	v_cvt_pk_bf16_f32 v145, v142, v143
	global_store_dwordx2 v11, v[144:145], s[24:25]
	s_add_u32 s24, s24, 0x800
	s_addc_u32 s25, s25, 0
	s_waitcnt vmcnt(9)
	v_and_b32_e32 v55, 0xffff0000, v53
	v_lshlrev_b32_e32 v54, 16, v53
	v_and_b32_e32 v53, 0xffff0000, v52
	v_lshlrev_b32_e32 v52, 16, v52
	v_add_f32_e32 v140, v52, v48
	v_add_f32_e32 v141, v53, v49
	v_add_f32_e32 v142, v54, v50
	v_add_f32_e32 v143, v55, v51
	v_add_f32_e32 v140, v140, v44
	v_add_f32_e32 v141, v141, v45
	v_add_f32_e32 v142, v142, v46
	v_add_f32_e32 v143, v143, v47
	v_add_f32_e32 v140, v140, v40
	v_add_f32_e32 v141, v141, v41
	v_add_f32_e32 v142, v142, v42
	v_add_f32_e32 v143, v143, v43
	v_mul_f32_e32 v140, 0x3e800000, v140
	v_mul_f32_e32 v141, 0x3e800000, v141
	v_mul_f32_e32 v142, 0x3e800000, v142
	v_mul_f32_e32 v143, 0x3e800000, v143
	v_sub_f32_e32 v140, v140, v52
	v_sub_f32_e32 v141, v141, v53
	v_sub_f32_e32 v142, v142, v54
	v_sub_f32_e32 v143, v143, v55
	v_cvt_pk_bf16_f32 v144, v140, v141
	v_cvt_pk_bf16_f32 v145, v142, v143
	global_store_dwordx2 v11, v[144:145], s[24:25]
	s_add_u32 s24, s24, 0x800
	s_addc_u32 s25, s25, 0
	s_waitcnt vmcnt(8)
	v_and_b32_e32 v59, 0xffff0000, v57
	v_lshlrev_b32_e32 v58, 16, v57
	v_and_b32_e32 v57, 0xffff0000, v56
	v_lshlrev_b32_e32 v56, 16, v56
	v_add_f32_e32 v140, v56, v52
	v_add_f32_e32 v141, v57, v53
	v_add_f32_e32 v142, v58, v54
	v_add_f32_e32 v143, v59, v55
	v_add_f32_e32 v140, v140, v48
	v_add_f32_e32 v141, v141, v49
	v_add_f32_e32 v142, v142, v50
	v_add_f32_e32 v143, v143, v51
	v_add_f32_e32 v140, v140, v44
	v_add_f32_e32 v141, v141, v45
	v_add_f32_e32 v142, v142, v46
	v_add_f32_e32 v143, v143, v47
	v_mul_f32_e32 v140, 0x3e800000, v140
	v_mul_f32_e32 v141, 0x3e800000, v141
	v_mul_f32_e32 v142, 0x3e800000, v142
	v_mul_f32_e32 v143, 0x3e800000, v143
	v_sub_f32_e32 v140, v140, v56
	v_sub_f32_e32 v141, v141, v57
	v_sub_f32_e32 v142, v142, v58
	v_sub_f32_e32 v143, v143, v59
	v_cvt_pk_bf16_f32 v144, v140, v141
	v_cvt_pk_bf16_f32 v145, v142, v143
	global_store_dwordx2 v11, v[144:145], s[24:25]
	s_add_u32 s24, s24, 0x800
	s_addc_u32 s25, s25, 0
	s_waitcnt vmcnt(7)
	v_and_b32_e32 v63, 0xffff0000, v61
	v_lshlrev_b32_e32 v62, 16, v61
	v_and_b32_e32 v61, 0xffff0000, v60
	v_lshlrev_b32_e32 v60, 16, v60
	v_add_f32_e32 v140, v60, v56
	v_add_f32_e32 v141, v61, v57
	v_add_f32_e32 v142, v62, v58
	v_add_f32_e32 v143, v63, v59
	v_add_f32_e32 v140, v140, v52
	v_add_f32_e32 v141, v141, v53
	v_add_f32_e32 v142, v142, v54
	v_add_f32_e32 v143, v143, v55
	v_add_f32_e32 v140, v140, v48
	v_add_f32_e32 v141, v141, v49
	v_add_f32_e32 v142, v142, v50
	v_add_f32_e32 v143, v143, v51
	v_mul_f32_e32 v140, 0x3e800000, v140
	v_mul_f32_e32 v141, 0x3e800000, v141
	v_mul_f32_e32 v142, 0x3e800000, v142
	v_mul_f32_e32 v143, 0x3e800000, v143
	v_sub_f32_e32 v140, v140, v60
	v_sub_f32_e32 v141, v141, v61
	v_sub_f32_e32 v142, v142, v62
	v_sub_f32_e32 v143, v143, v63
	v_cvt_pk_bf16_f32 v144, v140, v141
	v_cvt_pk_bf16_f32 v145, v142, v143
	global_store_dwordx2 v11, v[144:145], s[24:25]
	s_add_u32 s24, s24, 0x800
	s_addc_u32 s25, s25, 0
	s_waitcnt vmcnt(6)
; DI float bflo(unsigned u) { return __uint_as_float(u << 16); }
; DI float bfhi(unsigned u) { return __uint_as_float(u & 0xffff0000u); }
; template <int WIN>
; DI void pool_elem(const Params& p, int row, int c) {
;     ...
;     if (t >= WIN - 1) {
;       cnt = (float)WIN;
;       unsigned w[WIN - 1];
; #pragma unroll
;       for (int j = 1; j < WIN; ++j) w[j - 1] = *(const unsigned*)(P2 + (size_t)(row - j) * 2048 + c);
; #pragma unroll
;       for (int j = 1; j < WIN; ++j) { s0 += bflo(w[j - 1]); s1 += bfhi(w[j - 1]); }
;     ...
;   *(unsigned*)(p.MIX + (size_t)row * 1024 + c) = pack2(s0 / cnt - u0, s1 / cnt - u1);
	v_and_b32_e32 v67, 0xffff0000, v65
	v_lshlrev_b32_e32 v66, 16, v65
	v_and_b32_e32 v65, 0xffff0000, v64
	v_lshlrev_b32_e32 v64, 16, v64
	v_add_f32_e32 v140, v64, v60
	v_add_f32_e32 v141, v65, v61
	v_add_f32_e32 v142, v66, v62
	v_add_f32_e32 v143, v67, v63
	v_add_f32_e32 v140, v140, v56
	v_add_f32_e32 v141, v141, v57
	v_add_f32_e32 v142, v142, v58
	v_add_f32_e32 v143, v143, v59
	v_add_f32_e32 v140, v140, v52
	v_add_f32_e32 v141, v141, v53
	v_add_f32_e32 v142, v142, v54
	v_add_f32_e32 v143, v143, v55
	v_mul_f32_e32 v140, 0x3e800000, v140
	v_mul_f32_e32 v141, 0x3e800000, v141
	v_mul_f32_e32 v142, 0x3e800000, v142
	v_mul_f32_e32 v143, 0x3e800000, v143
	v_sub_f32_e32 v140, v140, v64
	v_sub_f32_e32 v141, v141, v65
	v_sub_f32_e32 v142, v142, v66
	v_sub_f32_e32 v143, v143, v67
	v_cvt_pk_bf16_f32 v144, v140, v141
	v_cvt_pk_bf16_f32 v145, v142, v143
	global_store_dwordx2 v11, v[144:145], s[24:25]
	s_add_u32 s24, s24, 0x800
	s_addc_u32 s25, s25, 0
	s_waitcnt vmcnt(5)
	v_and_b32_e32 v71, 0xffff0000, v69
	v_lshlrev_b32_e32 v70, 16, v69
	v_and_b32_e32 v69, 0xffff0000, v68
	v_lshlrev_b32_e32 v68, 16, v68
	v_add_f32_e32 v140, v68, v64
	v_add_f32_e32 v141, v69, v65
	v_add_f32_e32 v142, v70, v66
	v_add_f32_e32 v143, v71, v67
	v_add_f32_e32 v140, v140, v60
	v_add_f32_e32 v141, v141, v61
	v_add_f32_e32 v142, v142, v62
	v_add_f32_e32 v143, v143, v63
	v_add_f32_e32 v140, v140, v56
	v_add_f32_e32 v141, v141, v57
	v_add_f32_e32 v142, v142, v58
	v_add_f32_e32 v143, v143, v59
	v_mul_f32_e32 v140, 0x3e800000, v140
	v_mul_f32_e32 v141, 0x3e800000, v141
	v_mul_f32_e32 v142, 0x3e800000, v142
	v_mul_f32_e32 v143, 0x3e800000, v143
	v_sub_f32_e32 v140, v140, v68
	v_sub_f32_e32 v141, v141, v69
	v_sub_f32_e32 v142, v142, v70
	v_sub_f32_e32 v143, v143, v71
	v_cvt_pk_bf16_f32 v144, v140, v141
	v_cvt_pk_bf16_f32 v145, v142, v143
	global_store_dwordx2 v11, v[144:145], s[24:25]
	s_add_u32 s24, s24, 0x800
	s_addc_u32 s25, s25, 0
	s_waitcnt vmcnt(4)
	v_and_b32_e32 v75, 0xffff0000, v73
	v_lshlrev_b32_e32 v74, 16, v73
	v_and_b32_e32 v73, 0xffff0000, v72
	v_lshlrev_b32_e32 v72, 16, v72
	v_add_f32_e32 v140, v72, v68
	v_add_f32_e32 v141, v73, v69
	v_add_f32_e32 v142, v74, v70
	v_add_f32_e32 v143, v75, v71
	v_add_f32_e32 v140, v140, v64
	v_add_f32_e32 v141, v141, v65
	v_add_f32_e32 v142, v142, v66
	v_add_f32_e32 v143, v143, v67
	v_add_f32_e32 v140, v140, v60
	v_add_f32_e32 v141, v141, v61
	v_add_f32_e32 v142, v142, v62
	v_add_f32_e32 v143, v143, v63
	v_mul_f32_e32 v140, 0x3e800000, v140
	v_mul_f32_e32 v141, 0x3e800000, v141
	v_mul_f32_e32 v142, 0x3e800000, v142
	v_mul_f32_e32 v143, 0x3e800000, v143
	v_sub_f32_e32 v140, v140, v72
	v_sub_f32_e32 v141, v141, v73
	v_sub_f32_e32 v142, v142, v74
	v_sub_f32_e32 v143, v143, v75
	v_cvt_pk_bf16_f32 v144, v140, v141
	v_cvt_pk_bf16_f32 v145, v142, v143
	global_store_dwordx2 v11, v[144:145], s[24:25]
	s_add_u32 s24, s24, 0x800
	s_addc_u32 s25, s25, 0
	s_waitcnt vmcnt(3)
	v_and_b32_e32 v79, 0xffff0000, v77
	v_lshlrev_b32_e32 v78, 16, v77
	v_and_b32_e32 v77, 0xffff0000, v76
	v_lshlrev_b32_e32 v76, 16, v76
	v_add_f32_e32 v140, v76, v72
	v_add_f32_e32 v141, v77, v73
	v_add_f32_e32 v142, v78, v74
	v_add_f32_e32 v143, v79, v75
	v_add_f32_e32 v140, v140, v68
	v_add_f32_e32 v141, v141, v69
	v_add_f32_e32 v142, v142, v70
	v_add_f32_e32 v143, v143, v71
	v_add_f32_e32 v140, v140, v64
	v_add_f32_e32 v141, v141, v65
	v_add_f32_e32 v142, v142, v66
	v_add_f32_e32 v143, v143, v67
	v_mul_f32_e32 v140, 0x3e800000, v140
	v_mul_f32_e32 v141, 0x3e800000, v141
	v_mul_f32_e32 v142, 0x3e800000, v142
	v_mul_f32_e32 v143, 0x3e800000, v143
	v_sub_f32_e32 v140, v140, v76
	v_sub_f32_e32 v141, v141, v77
	v_sub_f32_e32 v142, v142, v78
	v_sub_f32_e32 v143, v143, v79
	v_cvt_pk_bf16_f32 v144, v140, v141
	v_cvt_pk_bf16_f32 v145, v142, v143
	global_store_dwordx2 v11, v[144:145], s[24:25]
	s_add_u32 s24, s24, 0x800
	s_addc_u32 s25, s25, 0
	s_waitcnt vmcnt(2)
	v_and_b32_e32 v83, 0xffff0000, v81
	v_lshlrev_b32_e32 v82, 16, v81
	v_and_b32_e32 v81, 0xffff0000, v80
	v_lshlrev_b32_e32 v80, 16, v80
	v_add_f32_e32 v140, v80, v76
	v_add_f32_e32 v141, v81, v77
	v_add_f32_e32 v142, v82, v78
	v_add_f32_e32 v143, v83, v79
	v_add_f32_e32 v140, v140, v72
	v_add_f32_e32 v141, v141, v73
	v_add_f32_e32 v142, v142, v74
	v_add_f32_e32 v143, v143, v75
	v_add_f32_e32 v140, v140, v68
	v_add_f32_e32 v141, v141, v69
	v_add_f32_e32 v142, v142, v70
	v_add_f32_e32 v143, v143, v71
	v_mul_f32_e32 v140, 0x3e800000, v140
	v_mul_f32_e32 v141, 0x3e800000, v141
	v_mul_f32_e32 v142, 0x3e800000, v142
	v_mul_f32_e32 v143, 0x3e800000, v143
	v_sub_f32_e32 v140, v140, v80
	v_sub_f32_e32 v141, v141, v81
	v_sub_f32_e32 v142, v142, v82
	v_sub_f32_e32 v143, v143, v83
	v_cvt_pk_bf16_f32 v144, v140, v141
	v_cvt_pk_bf16_f32 v145, v142, v143
	global_store_dwordx2 v11, v[144:145], s[24:25]
	s_add_u32 s24, s24, 0x800
	s_addc_u32 s25, s25, 0
	s_waitcnt vmcnt(1)
	v_and_b32_e32 v87, 0xffff0000, v85
	v_lshlrev_b32_e32 v86, 16, v85
	v_and_b32_e32 v85, 0xffff0000, v84
	v_lshlrev_b32_e32 v84, 16, v84
	v_add_f32_e32 v140, v84, v80
	v_add_f32_e32 v141, v85, v81
	v_add_f32_e32 v142, v86, v82
	v_add_f32_e32 v143, v87, v83
	v_add_f32_e32 v140, v140, v76
	v_add_f32_e32 v141, v141, v77
	v_add_f32_e32 v142, v142, v78
	v_add_f32_e32 v143, v143, v79
	v_add_f32_e32 v140, v140, v72
	v_add_f32_e32 v141, v141, v73
	v_add_f32_e32 v142, v142, v74
	v_add_f32_e32 v143, v143, v75
	v_mul_f32_e32 v140, 0x3e800000, v140
	v_mul_f32_e32 v141, 0x3e800000, v141
	v_mul_f32_e32 v142, 0x3e800000, v142
	v_mul_f32_e32 v143, 0x3e800000, v143
	v_sub_f32_e32 v140, v140, v84
	v_sub_f32_e32 v141, v141, v85
	v_sub_f32_e32 v142, v142, v86
	v_sub_f32_e32 v143, v143, v87
	v_cvt_pk_bf16_f32 v144, v140, v141
	v_cvt_pk_bf16_f32 v145, v142, v143
	global_store_dwordx2 v11, v[144:145], s[24:25]
	s_add_u32 s24, s24, 0x800
	s_addc_u32 s25, s25, 0
	s_waitcnt vmcnt(0)
	v_and_b32_e32 v91, 0xffff0000, v89
	v_lshlrev_b32_e32 v90, 16, v89
	v_and_b32_e32 v89, 0xffff0000, v88
	v_lshlrev_b32_e32 v88, 16, v88
	v_add_f32_e32 v140, v88, v84
	v_add_f32_e32 v141, v89, v85
	v_add_f32_e32 v142, v90, v86
	v_add_f32_e32 v143, v91, v87
	v_add_f32_e32 v140, v140, v80
	v_add_f32_e32 v141, v141, v81
	v_add_f32_e32 v142, v142, v82
	v_add_f32_e32 v143, v143, v83
	v_add_f32_e32 v140, v140, v76
	v_add_f32_e32 v141, v141, v77
	v_add_f32_e32 v142, v142, v78
	v_add_f32_e32 v143, v143, v79
	v_mul_f32_e32 v140, 0x3e800000, v140
	v_mul_f32_e32 v141, 0x3e800000, v141
	v_mul_f32_e32 v142, 0x3e800000, v142
	v_mul_f32_e32 v143, 0x3e800000, v143
	v_sub_f32_e32 v140, v140, v88
	v_sub_f32_e32 v141, v141, v89
	v_sub_f32_e32 v142, v142, v90
	v_sub_f32_e32 v143, v143, v91
	v_cvt_pk_bf16_f32 v144, v140, v141
	v_cvt_pk_bf16_f32 v145, v142, v143
	global_store_dwordx2 v11, v[144:145], s[24:25]
	s_add_u32 s24, s24, 0x800
	s_addc_u32 s25, s25, 0
	s_cmp_eq_u32 s18, 126
	s_cbranch_scc0 .Lp13f_next1
	s_mul_i32 s26, s17, 61440
	s_add_u32 s26, s26, 0x431c000
	s_add_u32 s22, s12, s26
	s_addc_u32 s23, s13, 0
	global_store_dwordx4 v12, v[32:35], s[22:23]
	s_add_u32 s22, s22, 0x1000
	s_addc_u32 s23, s23, 0
	global_store_dwordx4 v12, v[36:39], s[22:23]
	s_add_u32 s22, s22, 0x1000
	s_addc_u32 s23, s23, 0
	global_store_dwordx4 v12, v[40:43], s[22:23]
	s_add_u32 s22, s22, 0x1000
	s_addc_u32 s23, s23, 0
	global_store_dwordx4 v12, v[44:47], s[22:23]
	s_add_u32 s22, s22, 0x1000
	s_addc_u32 s23, s23, 0
	global_store_dwordx4 v12, v[48:51], s[22:23]
	s_add_u32 s22, s22, 0x1000
	s_addc_u32 s23, s23, 0
	global_store_dwordx4 v12, v[52:55], s[22:23]
	s_add_u32 s22, s22, 0x1000
	s_addc_u32 s23, s23, 0
	global_store_dwordx4 v12, v[56:59], s[22:23]
	s_add_u32 s22, s22, 0x1000
	s_addc_u32 s23, s23, 0
	global_store_dwordx4 v12, v[60:63], s[22:23]
	s_add_u32 s22, s22, 0x1000
	s_addc_u32 s23, s23, 0
	global_store_dwordx4 v12, v[64:67], s[22:23]
	s_add_u32 s22, s22, 0x1000
	s_addc_u32 s23, s23, 0
	global_store_dwordx4 v12, v[68:71], s[22:23]
	s_add_u32 s22, s22, 0x1000
	s_addc_u32 s23, s23, 0
	global_store_dwordx4 v12, v[72:75], s[22:23]
	s_add_u32 s22, s22, 0x1000
	s_addc_u32 s23, s23, 0
	global_store_dwordx4 v12, v[76:79], s[22:23]
	s_add_u32 s22, s22, 0x1000
	s_addc_u32 s23, s23, 0
	global_store_dwordx4 v12, v[80:83], s[22:23]
	s_add_u32 s22, s22, 0x1000
	s_addc_u32 s23, s23, 0
	global_store_dwordx4 v12, v[84:87], s[22:23]
	s_add_u32 s22, s22, 0x1000
	s_addc_u32 s23, s23, 0
	global_store_dwordx4 v12, v[88:91], s[22:23]
	s_add_u32 s22, s22, 0x1000
	s_addc_u32 s23, s23, 0

.Lp13f_w2:
	s_sub_u32 s26, s20, 7
	s_lshl_b32 s27, s26, 12
	s_lshr_b32 s28, s26, 20
	s_add_u32 s22, s8, s27
	s_addc_u32 s23, s9, s28
	global_load_dwordx2 v[16:17], v11, s[22:23]
	s_add_u32 s22, s22, 0x1000
	s_addc_u32 s23, s23, 0
	global_load_dwordx2 v[20:21], v11, s[22:23]
	s_add_u32 s22, s22, 0x1000
	s_addc_u32 s23, s23, 0
	global_load_dwordx2 v[24:25], v11, s[22:23]
	s_add_u32 s22, s22, 0x1000
	s_addc_u32 s23, s23, 0
	global_load_dwordx2 v[28:29], v11, s[22:23]
	s_add_u32 s22, s22, 0x1000
	s_addc_u32 s23, s23, 0
	global_load_dwordx2 v[32:33], v11, s[22:23]
	s_add_u32 s22, s22, 0x1000
	s_addc_u32 s23, s23, 0
	global_load_dwordx2 v[36:37], v11, s[22:23]
	s_add_u32 s22, s22, 0x1000
	s_addc_u32 s23, s23, 0
	global_load_dwordx2 v[40:41], v11, s[22:23]
	s_add_u32 s22, s22, 0x1000
	s_addc_u32 s23, s23, 0
	global_load_dwordx2 v[44:45], v11, s[22:23]
	s_add_u32 s22, s22, 0x1000
	s_addc_u32 s23, s23, 0
	global_load_dwordx2 v[48:49], v11, s[22:23]
	s_add_u32 s22, s22, 0x1000
	s_addc_u32 s23, s23, 0
	global_load_dwordx2 v[52:53], v11, s[22:23]
	s_add_u32 s22, s22, 0x1000
	s_addc_u32 s23, s23, 0
	global_load_dwordx2 v[56:57], v11, s[22:23]
	s_add_u32 s22, s22, 0x1000
	s_addc_u32 s23, s23, 0
	global_load_dwordx2 v[60:61], v11, s[22:23]
	s_add_u32 s22, s22, 0x1000
	s_addc_u32 s23, s23, 0
	global_load_dwordx2 v[64:65], v11, s[22:23]
	s_add_u32 s22, s22, 0x1000
	s_addc_u32 s23, s23, 0
	global_load_dwordx2 v[68:69], v11, s[22:23]
	s_add_u32 s22, s22, 0x1000
	s_addc_u32 s23, s23, 0
	global_load_dwordx2 v[72:73], v11, s[22:23]
	s_add_u32 s22, s22, 0x1000
	s_addc_u32 s23, s23, 0
	global_load_dwordx2 v[76:77], v11, s[22:23]
	s_add_u32 s22, s22, 0x1000
	s_addc_u32 s23, s23, 0
	global_load_dwordx2 v[80:81], v11, s[22:23]
	s_add_u32 s22, s22, 0x1000
	s_addc_u32 s23, s23, 0
	global_load_dwordx2 v[84:85], v11, s[22:23]
	s_add_u32 s22, s22, 0x1000
	s_addc_u32 s23, s23, 0
	global_load_dwordx2 v[88:89], v11, s[22:23]
	s_add_u32 s22, s22, 0x1000
	s_addc_u32 s23, s23, 0
	global_load_dwordx2 v[92:93], v11, s[22:23]
	s_add_u32 s22, s22, 0x1000
	s_addc_u32 s23, s23, 0
	global_load_dwordx2 v[96:97], v11, s[22:23]
	s_add_u32 s22, s22, 0x1000
	s_addc_u32 s23, s23, 0
	global_load_dwordx2 v[100:101], v11, s[22:23]
	s_add_u32 s22, s22, 0x1000
	s_addc_u32 s23, s23, 0
	global_load_dwordx2 v[104:105], v11, s[22:23]
	s_add_u32 s22, s22, 0x1000
	s_addc_u32 s23, s23, 0
	s_waitcnt vmcnt(15)
	v_and_b32_e32 v19, 0xffff0000, v17
	v_lshlrev_b32_e32 v18, 16, v17
	v_and_b32_e32 v17, 0xffff0000, v16
	v_lshlrev_b32_e32 v16, 16, v16
	v_and_b32_e32 v23, 0xffff0000, v21
	v_lshlrev_b32_e32 v22, 16, v21
	v_and_b32_e32 v21, 0xffff0000, v20
	v_lshlrev_b32_e32 v20, 16, v20
	v_and_b32_e32 v27, 0xffff0000, v25
	v_lshlrev_b32_e32 v26, 16, v25
	v_and_b32_e32 v25, 0xffff0000, v24
	v_lshlrev_b32_e32 v24, 16, v24
	v_and_b32_e32 v31, 0xffff0000, v29
	v_lshlrev_b32_e32 v30, 16, v29
	v_and_b32_e32 v29, 0xffff0000, v28
	v_lshlrev_b32_e32 v28, 16, v28
	v_and_b32_e32 v35, 0xffff0000, v33
	v_lshlrev_b32_e32 v34, 16, v33
	v_and_b32_e32 v33, 0xffff0000, v32
	v_lshlrev_b32_e32 v32, 16, v32
	v_and_b32_e32 v39, 0xffff0000, v37
	v_lshlrev_b32_e32 v38, 16, v37
	v_and_b32_e32 v37, 0xffff0000, v36
	v_lshlrev_b32_e32 v36, 16, v36
	v_and_b32_e32 v43, 0xffff0000, v41
	v_lshlrev_b32_e32 v42, 16, v41
	v_and_b32_e32 v41, 0xffff0000, v40
	v_lshlrev_b32_e32 v40, 16, v40
	v_and_b32_e32 v47, 0xffff0000, v45
	v_lshlrev_b32_e32 v46, 16, v45
	v_and_b32_e32 v45, 0xffff0000, v44
	v_lshlrev_b32_e32 v44, 16, v44
	v_add_f32_e32 v140, v44, v40
	v_add_f32_e32 v141, v45, v41
	v_add_f32_e32 v142, v46, v42
	v_add_f32_e32 v143, v47, v43
	v_add_f32_e32 v140, v140, v36
	v_add_f32_e32 v141, v141, v37
	v_add_f32_e32 v142, v142, v38
	v_add_f32_e32 v143, v143, v39
	v_add_f32_e32 v140, v140, v32
	v_add_f32_e32 v141, v141, v33
	v_add_f32_e32 v142, v142, v34
	v_add_f32_e32 v143, v143, v35
	v_add_f32_e32 v140, v140, v28
	v_add_f32_e32 v141, v141, v29
	v_add_f32_e32 v142, v142, v30
	v_add_f32_e32 v143, v143, v31
	v_add_f32_e32 v140, v140, v24
	v_add_f32_e32 v141, v141, v25
	v_add_f32_e32 v142, v142, v26
	v_add_f32_e32 v143, v143, v27
	v_add_f32_e32 v140, v140, v20
	v_add_f32_e32 v141, v141, v21
	v_add_f32_e32 v142, v142, v22
	v_add_f32_e32 v143, v143, v23
	v_add_f32_e32 v140, v140, v16
	v_add_f32_e32 v141, v141, v17
	v_add_f32_e32 v142, v142, v18
	v_add_f32_e32 v143, v143, v19
	v_mul_f32_e32 v140, 0x3e000000, v140
	v_mul_f32_e32 v141, 0x3e000000, v141
	v_mul_f32_e32 v142, 0x3e000000, v142
	v_mul_f32_e32 v143, 0x3e000000, v143
	v_sub_f32_e32 v140, v140, v44
	v_sub_f32_e32 v141, v141, v45
	v_sub_f32_e32 v142, v142, v46
	v_sub_f32_e32 v143, v143, v47
	v_cvt_pk_bf16_f32 v144, v140, v141
	v_cvt_pk_bf16_f32 v145, v142, v143
	global_store_dwordx2 v11, v[144:145], s[24:25]
	s_add_u32 s24, s24, 0x800
	s_addc_u32 s25, s25, 0
	s_waitcnt vmcnt(14)
	v_and_b32_e32 v51, 0xffff0000, v49
	v_lshlrev_b32_e32 v50, 16, v49
	v_and_b32_e32 v49, 0xffff0000, v48
	v_lshlrev_b32_e32 v48, 16, v48
	v_add_f32_e32 v140, v48, v44
	v_add_f32_e32 v141, v49, v45
	v_add_f32_e32 v142, v50, v46
	v_add_f32_e32 v143, v51, v47
	v_add_f32_e32 v140, v140, v40
	v_add_f32_e32 v141, v141, v41
	v_add_f32_e32 v142, v142, v42
	v_add_f32_e32 v143, v143, v43
	v_add_f32_e32 v140, v140, v36
	v_add_f32_e32 v141, v141, v37
	v_add_f32_e32 v142, v142, v38
	v_add_f32_e32 v143, v143, v39
	v_add_f32_e32 v140, v140, v32
	v_add_f32_e32 v141, v141, v33
	v_add_f32_e32 v142, v142, v34
	v_add_f32_e32 v143, v143, v35
	v_add_f32_e32 v140, v140, v28
	v_add_f32_e32 v141, v141, v29
	v_add_f32_e32 v142, v142, v30
	v_add_f32_e32 v143, v143, v31
	v_add_f32_e32 v140, v140, v24
	v_add_f32_e32 v141, v141, v25
	v_add_f32_e32 v142, v142, v26
	v_add_f32_e32 v143, v143, v27
	v_add_f32_e32 v140, v140, v20
	v_add_f32_e32 v141, v141, v21
	v_add_f32_e32 v142, v142, v22
	v_add_f32_e32 v143, v143, v23
	v_mul_f32_e32 v140, 0x3e000000, v140
	v_mul_f32_e32 v141, 0x3e000000, v141
	v_mul_f32_e32 v142, 0x3e000000, v142
	v_mul_f32_e32 v143, 0x3e000000, v143
	v_sub_f32_e32 v140, v140, v48
	v_sub_f32_e32 v141, v141, v49
	v_sub_f32_e32 v142, v142, v50
	v_sub_f32_e32 v143, v143, v51
	v_cvt_pk_bf16_f32 v144, v140, v141
	v_cvt_pk_bf16_f32 v145, v142, v143
	global_store_dwordx2 v11, v[144:145], s[24:25]
	s_add_u32 s24, s24, 0x800
	s_addc_u32 s25, s25, 0
	s_waitcnt vmcnt(13)
	v_and_b32_e32 v55, 0xffff0000, v53
	v_lshlrev_b32_e32 v54, 16, v53
	v_and_b32_e32 v53, 0xffff0000, v52
	v_lshlrev_b32_e32 v52, 16, v52
	v_add_f32_e32 v140, v52, v48
	v_add_f32_e32 v141, v53, v49
	v_add_f32_e32 v142, v54, v50
	v_add_f32_e32 v143, v55, v51
	v_add_f32_e32 v140, v140, v44
	v_add_f32_e32 v141, v141, v45
	v_add_f32_e32 v142, v142, v46
	v_add_f32_e32 v143, v143, v47
	v_add_f32_e32 v140, v140, v40
	v_add_f32_e32 v141, v141, v41
	v_add_f32_e32 v142, v142, v42
	v_add_f32_e32 v143, v143, v43
	v_add_f32_e32 v140, v140, v36
	v_add_f32_e32 v141, v141, v37
	v_add_f32_e32 v142, v142, v38
	v_add_f32_e32 v143, v143, v39
	v_add_f32_e32 v140, v140, v32
	v_add_f32_e32 v141, v141, v33
	v_add_f32_e32 v142, v142, v34
	v_add_f32_e32 v143, v143, v35
	v_add_f32_e32 v140, v140, v28
	v_add_f32_e32 v141, v141, v29
	v_add_f32_e32 v142, v142, v30
	v_add_f32_e32 v143, v143, v31
	v_add_f32_e32 v140, v140, v24
	v_add_f32_e32 v141, v141, v25
	v_add_f32_e32 v142, v142, v26
	v_add_f32_e32 v143, v143, v27
	v_mul_f32_e32 v140, 0x3e000000, v140
	v_mul_f32_e32 v141, 0x3e000000, v141
	v_mul_f32_e32 v142, 0x3e000000, v142
	v_mul_f32_e32 v143, 0x3e000000, v143
	v_sub_f32_e32 v140, v140, v52
	v_sub_f32_e32 v141, v141, v53
	v_sub_f32_e32 v142, v142, v54
	v_sub_f32_e32 v143, v143, v55
	v_cvt_pk_bf16_f32 v144, v140, v141
	v_cvt_pk_bf16_f32 v145, v142, v143
	global_store_dwordx2 v11, v[144:145], s[24:25]
	s_add_u32 s24, s24, 0x800
	s_addc_u32 s25, s25, 0
	s_waitcnt vmcnt(12)
	v_and_b32_e32 v59, 0xffff0000, v57
	v_lshlrev_b32_e32 v58, 16, v57
	v_and_b32_e32 v57, 0xffff0000, v56
	v_lshlrev_b32_e32 v56, 16, v56
	v_add_f32_e32 v140, v56, v52
	v_add_f32_e32 v141, v57, v53
	v_add_f32_e32 v142, v58, v54
	v_add_f32_e32 v143, v59, v55
	v_add_f32_e32 v140, v140, v48
	v_add_f32_e32 v141, v141, v49
	v_add_f32_e32 v142, v142, v50
	v_add_f32_e32 v143, v143, v51
	v_add_f32_e32 v140, v140, v44
	v_add_f32_e32 v141, v141, v45
	v_add_f32_e32 v142, v142, v46
	v_add_f32_e32 v143, v143, v47
	v_add_f32_e32 v140, v140, v40
	v_add_f32_e32 v141, v141, v41
	v_add_f32_e32 v142, v142, v42
	v_add_f32_e32 v143, v143, v43
	v_add_f32_e32 v140, v140, v36
	v_add_f32_e32 v141, v141, v37
	v_add_f32_e32 v142, v142, v38
	v_add_f32_e32 v143, v143, v39
	v_add_f32_e32 v140, v140, v32
	v_add_f32_e32 v141, v141, v33
	v_add_f32_e32 v142, v142, v34
	v_add_f32_e32 v143, v143, v35
	v_add_f32_e32 v140, v140, v28
	v_add_f32_e32 v141, v141, v29
	v_add_f32_e32 v142, v142, v30
	v_add_f32_e32 v143, v143, v31
	v_mul_f32_e32 v140, 0x3e000000, v140
	v_mul_f32_e32 v141, 0x3e000000, v141
	v_mul_f32_e32 v142, 0x3e000000, v142
	v_mul_f32_e32 v143, 0x3e000000, v143
	v_sub_f32_e32 v140, v140, v56
	v_sub_f32_e32 v141, v141, v57
	v_sub_f32_e32 v142, v142, v58
	v_sub_f32_e32 v143, v143, v59
	v_cvt_pk_bf16_f32 v144, v140, v141
	v_cvt_pk_bf16_f32 v145, v142, v143
	global_store_dwordx2 v11, v[144:145], s[24:25]
	s_add_u32 s24, s24, 0x800
	s_addc_u32 s25, s25, 0
	s_waitcnt vmcnt(11)
	v_and_b32_e32 v63, 0xffff0000, v61
	v_lshlrev_b32_e32 v62, 16, v61
	v_and_b32_e32 v61, 0xffff0000, v60
	v_lshlrev_b32_e32 v60, 16, v60
	v_add_f32_e32 v140, v60, v56
	v_add_f32_e32 v141, v61, v57
	v_add_f32_e32 v142, v62, v58
	v_add_f32_e32 v143, v63, v59
	v_add_f32_e32 v140, v140, v52
	v_add_f32_e32 v141, v141, v53
	v_add_f32_e32 v142, v142, v54
	v_add_f32_e32 v143, v143, v55
	v_add_f32_e32 v140, v140, v48
	v_add_f32_e32 v141, v141, v49
	v_add_f32_e32 v142, v142, v50
	v_add_f32_e32 v143, v143, v51
	v_add_f32_e32 v140, v140, v44
	v_add_f32_e32 v141, v141, v45
	v_add_f32_e32 v142, v142, v46
	v_add_f32_e32 v143, v143, v47
	v_add_f32_e32 v140, v140, v40
	v_add_f32_e32 v141, v141, v41
	v_add_f32_e32 v142, v142, v42
	v_add_f32_e32 v143, v143, v43
	v_add_f32_e32 v140, v140, v36
	v_add_f32_e32 v141, v141, v37
	v_add_f32_e32 v142, v142, v38
	v_add_f32_e32 v143, v143, v39
	v_add_f32_e32 v140, v140, v32
	v_add_f32_e32 v141, v141, v33
	v_add_f32_e32 v142, v142, v34
	v_add_f32_e32 v143, v143, v35
	v_mul_f32_e32 v140, 0x3e000000, v140
	v_mul_f32_e32 v141, 0x3e000000, v141
	v_mul_f32_e32 v142, 0x3e000000, v142
	v_mul_f32_e32 v143, 0x3e000000, v143
	v_sub_f32_e32 v140, v140, v60
	v_sub_f32_e32 v141, v141, v61
	v_sub_f32_e32 v142, v142, v62
	v_sub_f32_e32 v143, v143, v63
	v_cvt_pk_bf16_f32 v144, v140, v141
	v_cvt_pk_bf16_f32 v145, v142, v143
	global_store_dwordx2 v11, v[144:145], s[24:25]
	s_add_u32 s24, s24, 0x800
	s_addc_u32 s25, s25, 0
	s_waitcnt vmcnt(10)
	v_and_b32_e32 v67, 0xffff0000, v65
	v_lshlrev_b32_e32 v66, 16, v65
	v_and_b32_e32 v65, 0xffff0000, v64
	v_lshlrev_b32_e32 v64, 16, v64
	v_add_f32_e32 v140, v64, v60
	v_add_f32_e32 v141, v65, v61
	v_add_f32_e32 v142, v66, v62
	v_add_f32_e32 v143, v67, v63
	v_add_f32_e32 v140, v140, v56
	v_add_f32_e32 v141, v141, v57
	v_add_f32_e32 v142, v142, v58
	v_add_f32_e32 v143, v143, v59
	v_add_f32_e32 v140, v140, v52
	v_add_f32_e32 v141, v141, v53
	v_add_f32_e32 v142, v142, v54
	v_add_f32_e32 v143, v143, v55
	v_add_f32_e32 v140, v140, v48
	v_add_f32_e32 v141, v141, v49
	v_add_f32_e32 v142, v142, v50
	v_add_f32_e32 v143, v143, v51
	v_add_f32_e32 v140, v140, v44
	v_add_f32_e32 v141, v141, v45
	v_add_f32_e32 v142, v142, v46
	v_add_f32_e32 v143, v143, v47
	v_add_f32_e32 v140, v140, v40
	v_add_f32_e32 v141, v141, v41
	v_add_f32_e32 v142, v142, v42
	v_add_f32_e32 v143, v143, v43
	v_add_f32_e32 v140, v140, v36
	v_add_f32_e32 v141, v141, v37
	v_add_f32_e32 v142, v142, v38
	v_add_f32_e32 v143, v143, v39
	v_mul_f32_e32 v140, 0x3e000000, v140
	v_mul_f32_e32 v141, 0x3e000000, v141
	v_mul_f32_e32 v142, 0x3e000000, v142
	v_mul_f32_e32 v143, 0x3e000000, v143
	v_sub_f32_e32 v140, v140, v64
	v_sub_f32_e32 v141, v141, v65
	v_sub_f32_e32 v142, v142, v66
	v_sub_f32_e32 v143, v143, v67
	v_cvt_pk_bf16_f32 v144, v140, v141
	v_cvt_pk_bf16_f32 v145, v142, v143
	global_store_dwordx2 v11, v[144:145], s[24:25]
	s_add_u32 s24, s24, 0x800
	s_addc_u32 s25, s25, 0
	s_waitcnt vmcnt(9)
	v_and_b32_e32 v71, 0xffff0000, v69
	v_lshlrev_b32_e32 v70, 16, v69
	v_and_b32_e32 v69, 0xffff0000, v68
	v_lshlrev_b32_e32 v68, 16, v68
	v_add_f32_e32 v140, v68, v64
	v_add_f32_e32 v141, v69, v65
	v_add_f32_e32 v142, v70, v66
	v_add_f32_e32 v143, v71, v67
	v_add_f32_e32 v140, v140, v60
	v_add_f32_e32 v141, v141, v61
	v_add_f32_e32 v142, v142, v62
	v_add_f32_e32 v143, v143, v63
	v_add_f32_e32 v140, v140, v56
	v_add_f32_e32 v141, v141, v57
	v_add_f32_e32 v142, v142, v58
	v_add_f32_e32 v143, v143, v59
	v_add_f32_e32 v140, v140, v52
	v_add_f32_e32 v141, v141, v53
	v_add_f32_e32 v142, v142, v54
	v_add_f32_e32 v143, v143, v55
	v_add_f32_e32 v140, v140, v48
	v_add_f32_e32 v141, v141, v49
	v_add_f32_e32 v142, v142, v50
	v_add_f32_e32 v143, v143, v51
	v_add_f32_e32 v140, v140, v44
	v_add_f32_e32 v141, v141, v45
	v_add_f32_e32 v142, v142, v46
	v_add_f32_e32 v143, v143, v47
	v_add_f32_e32 v140, v140, v40
	v_add_f32_e32 v141, v141, v41
	v_add_f32_e32 v142, v142, v42
	v_add_f32_e32 v143, v143, v43
	v_mul_f32_e32 v140, 0x3e000000, v140
	v_mul_f32_e32 v141, 0x3e000000, v141
	v_mul_f32_e32 v142, 0x3e000000, v142
	v_mul_f32_e32 v143, 0x3e000000, v143
	v_sub_f32_e32 v140, v140, v68
	v_sub_f32_e32 v141, v141, v69
	v_sub_f32_e32 v142, v142, v70
	v_sub_f32_e32 v143, v143, v71
	v_cvt_pk_bf16_f32 v144, v140, v141
	v_cvt_pk_bf16_f32 v145, v142, v143
	global_store_dwordx2 v11, v[144:145], s[24:25]
	s_add_u32 s24, s24, 0x800
	s_addc_u32 s25, s25, 0
	s_waitcnt vmcnt(8)
	v_and_b32_e32 v75, 0xffff0000, v73
	v_lshlrev_b32_e32 v74, 16, v73
	v_and_b32_e32 v73, 0xffff0000, v72
	v_lshlrev_b32_e32 v72, 16, v72
	v_add_f32_e32 v140, v72, v68
	v_add_f32_e32 v141, v73, v69
	v_add_f32_e32 v142, v74, v70
	v_add_f32_e32 v143, v75, v71
	v_add_f32_e32 v140, v140, v64
	v_add_f32_e32 v141, v141, v65
	v_add_f32_e32 v142, v142, v66
	v_add_f32_e32 v143, v143, v67
	v_add_f32_e32 v140, v140, v60
	v_add_f32_e32 v141, v141, v61
	v_add_f32_e32 v142, v142, v62
	v_add_f32_e32 v143, v143, v63
	v_add_f32_e32 v140, v140, v56
	v_add_f32_e32 v141, v141, v57
	v_add_f32_e32 v142, v142, v58
	v_add_f32_e32 v143, v143, v59
	v_add_f32_e32 v140, v140, v52
	v_add_f32_e32 v141, v141, v53
	v_add_f32_e32 v142, v142, v54
	v_add_f32_e32 v143, v143, v55
	v_add_f32_e32 v140, v140, v48
	v_add_f32_e32 v141, v141, v49
	v_add_f32_e32 v142, v142, v50
	v_add_f32_e32 v143, v143, v51
	v_add_f32_e32 v140, v140, v44
	v_add_f32_e32 v141, v141, v45
	v_add_f32_e32 v142, v142, v46
	v_add_f32_e32 v143, v143, v47
	v_mul_f32_e32 v140, 0x3e000000, v140
	v_mul_f32_e32 v141, 0x3e000000, v141
	v_mul_f32_e32 v142, 0x3e000000, v142
	v_mul_f32_e32 v143, 0x3e000000, v143
	v_sub_f32_e32 v140, v140, v72
	v_sub_f32_e32 v141, v141, v73
	v_sub_f32_e32 v142, v142, v74
	v_sub_f32_e32 v143, v143, v75
	v_cvt_pk_bf16_f32 v144, v140, v141
	v_cvt_pk_bf16_f32 v145, v142, v143
	global_store_dwordx2 v11, v[144:145], s[24:25]
	s_add_u32 s24, s24, 0x800
	s_addc_u32 s25, s25, 0
	s_waitcnt vmcnt(7)
	v_and_b32_e32 v79, 0xffff0000, v77
	v_lshlrev_b32_e32 v78, 16, v77
	v_and_b32_e32 v77, 0xffff0000, v76
	v_lshlrev_b32_e32 v76, 16, v76
	v_add_f32_e32 v140, v76, v72
	v_add_f32_e32 v141, v77, v73
	v_add_f32_e32 v142, v78, v74
	v_add_f32_e32 v143, v79, v75
	v_add_f32_e32 v140, v140, v68
	v_add_f32_e32 v141, v141, v69
	v_add_f32_e32 v142, v142, v70
	v_add_f32_e32 v143, v143, v71
	v_add_f32_e32 v140, v140, v64
	v_add_f32_e32 v141, v141, v65
	v_add_f32_e32 v142, v142, v66
	v_add_f32_e32 v143, v143, v67
	v_add_f32_e32 v140, v140, v60
	v_add_f32_e32 v141, v141, v61
	v_add_f32_e32 v142, v142, v62
	v_add_f32_e32 v143, v143, v63
	v_add_f32_e32 v140, v140, v56
	v_add_f32_e32 v141, v141, v57
	v_add_f32_e32 v142, v142, v58
	v_add_f32_e32 v143, v143, v59
	v_add_f32_e32 v140, v140, v52
	v_add_f32_e32 v141, v141, v53
	v_add_f32_e32 v142, v142, v54
	v_add_f32_e32 v143, v143, v55
	v_add_f32_e32 v140, v140, v48
	v_add_f32_e32 v141, v141, v49
	v_add_f32_e32 v142, v142, v50
	v_add_f32_e32 v143, v143, v51
	v_mul_f32_e32 v140, 0x3e000000, v140
	v_mul_f32_e32 v141, 0x3e000000, v141
	v_mul_f32_e32 v142, 0x3e000000, v142
	v_mul_f32_e32 v143, 0x3e000000, v143
	v_sub_f32_e32 v140, v140, v76
	v_sub_f32_e32 v141, v141, v77
	v_sub_f32_e32 v142, v142, v78
	v_sub_f32_e32 v143, v143, v79
	v_cvt_pk_bf16_f32 v144, v140, v141
	v_cvt_pk_bf16_f32 v145, v142, v143
	global_store_dwordx2 v11, v[144:145], s[24:25]
	s_add_u32 s24, s24, 0x800
	s_addc_u32 s25, s25, 0
	s_waitcnt vmcnt(6)
	v_and_b32_e32 v83, 0xffff0000, v81
	v_lshlrev_b32_e32 v82, 16, v81
	v_and_b32_e32 v81, 0xffff0000, v80
	v_lshlrev_b32_e32 v80, 16, v80
	v_add_f32_e32 v140, v80, v76
	v_add_f32_e32 v141, v81, v77
	v_add_f32_e32 v142, v82, v78
	v_add_f32_e32 v143, v83, v79
	v_add_f32_e32 v140, v140, v72
	v_add_f32_e32 v141, v141, v73
	v_add_f32_e32 v142, v142, v74
	v_add_f32_e32 v143, v143, v75
	v_add_f32_e32 v140, v140, v68
	v_add_f32_e32 v141, v141, v69
	v_add_f32_e32 v142, v142, v70
	v_add_f32_e32 v143, v143, v71
	v_add_f32_e32 v140, v140, v64
	v_add_f32_e32 v141, v141, v65
	v_add_f32_e32 v142, v142, v66
	v_add_f32_e32 v143, v143, v67
	v_add_f32_e32 v140, v140, v60
	v_add_f32_e32 v141, v141, v61
	v_add_f32_e32 v142, v142, v62
	v_add_f32_e32 v143, v143, v63
	v_add_f32_e32 v140, v140, v56
	v_add_f32_e32 v141, v141, v57
	v_add_f32_e32 v142, v142, v58
	v_add_f32_e32 v143, v143, v59
	v_add_f32_e32 v140, v140, v52
	v_add_f32_e32 v141, v141, v53
	v_add_f32_e32 v142, v142, v54
	v_add_f32_e32 v143, v143, v55
	v_mul_f32_e32 v140, 0x3e000000, v140
	v_mul_f32_e32 v141, 0x3e000000, v141
	v_mul_f32_e32 v142, 0x3e000000, v142
	v_mul_f32_e32 v143, 0x3e000000, v143
	v_sub_f32_e32 v140, v140, v80
	v_sub_f32_e32 v141, v141, v81
	v_sub_f32_e32 v142, v142, v82
	v_sub_f32_e32 v143, v143, v83
	v_cvt_pk_bf16_f32 v144, v140, v141
	v_cvt_pk_bf16_f32 v145, v142, v143
	global_store_dwordx2 v11, v[144:145], s[24:25]
	s_add_u32 s24, s24, 0x800
	s_addc_u32 s25, s25, 0
	s_waitcnt vmcnt(5)
	v_and_b32_e32 v87, 0xffff0000, v85
	v_lshlrev_b32_e32 v86, 16, v85
	v_and_b32_e32 v85, 0xffff0000, v84
	v_lshlrev_b32_e32 v84, 16, v84
	v_add_f32_e32 v140, v84, v80
	v_add_f32_e32 v141, v85, v81
	v_add_f32_e32 v142, v86, v82
	v_add_f32_e32 v143, v87, v83
	v_add_f32_e32 v140, v140, v76
	v_add_f32_e32 v141, v141, v77
	v_add_f32_e32 v142, v142, v78
	v_add_f32_e32 v143, v143, v79
	v_add_f32_e32 v140, v140, v72
	v_add_f32_e32 v141, v141, v73
	v_add_f32_e32 v142, v142, v74
	v_add_f32_e32 v143, v143, v75
	v_add_f32_e32 v140, v140, v68
	v_add_f32_e32 v141, v141, v69
	v_add_f32_e32 v142, v142, v70
	v_add_f32_e32 v143, v143, v71
	v_add_f32_e32 v140, v140, v64
	v_add_f32_e32 v141, v141, v65
	v_add_f32_e32 v142, v142, v66
	v_add_f32_e32 v143, v143, v67
	v_add_f32_e32 v140, v140, v60
	v_add_f32_e32 v141, v141, v61
	v_add_f32_e32 v142, v142, v62
	v_add_f32_e32 v143, v143, v63
	v_add_f32_e32 v140, v140, v56
	v_add_f32_e32 v141, v141, v57
	v_add_f32_e32 v142, v142, v58
	v_add_f32_e32 v143, v143, v59
	v_mul_f32_e32 v140, 0x3e000000, v140
	v_mul_f32_e32 v141, 0x3e000000, v141
	v_mul_f32_e32 v142, 0x3e000000, v142
	v_mul_f32_e32 v143, 0x3e000000, v143
	v_sub_f32_e32 v140, v140, v84
	v_sub_f32_e32 v141, v141, v85
	v_sub_f32_e32 v142, v142, v86
	v_sub_f32_e32 v143, v143, v87
	v_cvt_pk_bf16_f32 v144, v140, v141
	v_cvt_pk_bf16_f32 v145, v142, v143
	global_store_dwordx2 v11, v[144:145], s[24:25]
	s_add_u32 s24, s24, 0x800
	s_addc_u32 s25, s25, 0
	s_waitcnt vmcnt(4)
	v_and_b32_e32 v91, 0xffff0000, v89
	v_lshlrev_b32_e32 v90, 16, v89
	v_and_b32_e32 v89, 0xffff0000, v88
	v_lshlrev_b32_e32 v88, 16, v88
	v_add_f32_e32 v140, v88, v84
	v_add_f32_e32 v141, v89, v85
	v_add_f32_e32 v142, v90, v86
	v_add_f32_e32 v143, v91, v87
	v_add_f32_e32 v140, v140, v80
	v_add_f32_e32 v141, v141, v81
	v_add_f32_e32 v142, v142, v82
	v_add_f32_e32 v143, v143, v83
	v_add_f32_e32 v140, v140, v76
	v_add_f32_e32 v141, v141, v77
	v_add_f32_e32 v142, v142, v78
	v_add_f32_e32 v143, v143, v79
	v_add_f32_e32 v140, v140, v72
	v_add_f32_e32 v141, v141, v73
	v_add_f32_e32 v142, v142, v74
	v_add_f32_e32 v143, v143, v75
	v_add_f32_e32 v140, v140, v68
	v_add_f32_e32 v141, v141, v69
	v_add_f32_e32 v142, v142, v70
	v_add_f32_e32 v143, v143, v71
	v_add_f32_e32 v140, v140, v64
	v_add_f32_e32 v141, v141, v65
	v_add_f32_e32 v142, v142, v66
	v_add_f32_e32 v143, v143, v67
	v_add_f32_e32 v140, v140, v60
	v_add_f32_e32 v141, v141, v61
	v_add_f32_e32 v142, v142, v62
	v_add_f32_e32 v143, v143, v63
	v_mul_f32_e32 v140, 0x3e000000, v140
	v_mul_f32_e32 v141, 0x3e000000, v141
	v_mul_f32_e32 v142, 0x3e000000, v142
	v_mul_f32_e32 v143, 0x3e000000, v143
	v_sub_f32_e32 v140, v140, v88
	v_sub_f32_e32 v141, v141, v89
	v_sub_f32_e32 v142, v142, v90
	v_sub_f32_e32 v143, v143, v91
	v_cvt_pk_bf16_f32 v144, v140, v141
	v_cvt_pk_bf16_f32 v145, v142, v143
	global_store_dwordx2 v11, v[144:145], s[24:25]
	s_add_u32 s24, s24, 0x800
	s_addc_u32 s25, s25, 0
	s_waitcnt vmcnt(3)
	v_and_b32_e32 v95, 0xffff0000, v93
	v_lshlrev_b32_e32 v94, 16, v93
	v_and_b32_e32 v93, 0xffff0000, v92
	v_lshlrev_b32_e32 v92, 16, v92
	v_add_f32_e32 v140, v92, v88
	v_add_f32_e32 v141, v93, v89
	v_add_f32_e32 v142, v94, v90
	v_add_f32_e32 v143, v95, v91
	v_add_f32_e32 v140, v140, v84
	v_add_f32_e32 v141, v141, v85
	v_add_f32_e32 v142, v142, v86
	v_add_f32_e32 v143, v143, v87
	v_add_f32_e32 v140, v140, v80
	v_add_f32_e32 v141, v141, v81
	v_add_f32_e32 v142, v142, v82
	v_add_f32_e32 v143, v143, v83
	v_add_f32_e32 v140, v140, v76
	v_add_f32_e32 v141, v141, v77
	v_add_f32_e32 v142, v142, v78
	v_add_f32_e32 v143, v143, v79
	v_add_f32_e32 v140, v140, v72
	v_add_f32_e32 v141, v141, v73
	v_add_f32_e32 v142, v142, v74
	v_add_f32_e32 v143, v143, v75
	v_add_f32_e32 v140, v140, v68
	v_add_f32_e32 v141, v141, v69
	v_add_f32_e32 v142, v142, v70
	v_add_f32_e32 v143, v143, v71
	v_add_f32_e32 v140, v140, v64
	v_add_f32_e32 v141, v141, v65
	v_add_f32_e32 v142, v142, v66
	v_add_f32_e32 v143, v143, v67
	v_mul_f32_e32 v140, 0x3e000000, v140
	v_mul_f32_e32 v141, 0x3e000000, v141
	v_mul_f32_e32 v142, 0x3e000000, v142
	v_mul_f32_e32 v143, 0x3e000000, v143
	v_sub_f32_e32 v140, v140, v92
	v_sub_f32_e32 v141, v141, v93
	v_sub_f32_e32 v142, v142, v94
	v_sub_f32_e32 v143, v143, v95
	v_cvt_pk_bf16_f32 v144, v140, v141
	v_cvt_pk_bf16_f32 v145, v142, v143
	global_store_dwordx2 v11, v[144:145], s[24:25]
	s_add_u32 s24, s24, 0x800
	s_addc_u32 s25, s25, 0
	s_waitcnt vmcnt(2)
	v_and_b32_e32 v99, 0xffff0000, v97
	v_lshlrev_b32_e32 v98, 16, v97
	v_and_b32_e32 v97, 0xffff0000, v96
	v_lshlrev_b32_e32 v96, 16, v96
	v_add_f32_e32 v140, v96, v92
	v_add_f32_e32 v141, v97, v93
	v_add_f32_e32 v142, v98, v94
	v_add_f32_e32 v143, v99, v95
	v_add_f32_e32 v140, v140, v88
	v_add_f32_e32 v141, v141, v89
	v_add_f32_e32 v142, v142, v90
	v_add_f32_e32 v143, v143, v91
	v_add_f32_e32 v140, v140, v84
	v_add_f32_e32 v141, v141, v85
	v_add_f32_e32 v142, v142, v86
	v_add_f32_e32 v143, v143, v87
	v_add_f32_e32 v140, v140, v80
	v_add_f32_e32 v141, v141, v81
	v_add_f32_e32 v142, v142, v82
	v_add_f32_e32 v143, v143, v83
	v_add_f32_e32 v140, v140, v76
	v_add_f32_e32 v141, v141, v77
	v_add_f32_e32 v142, v142, v78
	v_add_f32_e32 v143, v143, v79
	v_add_f32_e32 v140, v140, v72
	v_add_f32_e32 v141, v141, v73
	v_add_f32_e32 v142, v142, v74
	v_add_f32_e32 v143, v143, v75
	v_add_f32_e32 v140, v140, v68
	v_add_f32_e32 v141, v141, v69
	v_add_f32_e32 v142, v142, v70
	v_add_f32_e32 v143, v143, v71
	v_mul_f32_e32 v140, 0x3e000000, v140
	v_mul_f32_e32 v141, 0x3e000000, v141
	v_mul_f32_e32 v142, 0x3e000000, v142
	v_mul_f32_e32 v143, 0x3e000000, v143
	v_sub_f32_e32 v140, v140, v96
	v_sub_f32_e32 v141, v141, v97
	v_sub_f32_e32 v142, v142, v98
	v_sub_f32_e32 v143, v143, v99
	v_cvt_pk_bf16_f32 v144, v140, v141
	v_cvt_pk_bf16_f32 v145, v142, v143
	global_store_dwordx2 v11, v[144:145], s[24:25]
	s_add_u32 s24, s24, 0x800
	s_addc_u32 s25, s25, 0
	s_waitcnt vmcnt(1)
	v_and_b32_e32 v103, 0xffff0000, v101
	v_lshlrev_b32_e32 v102, 16, v101
	v_and_b32_e32 v101, 0xffff0000, v100
	v_lshlrev_b32_e32 v100, 16, v100
	v_add_f32_e32 v140, v100, v96
	v_add_f32_e32 v141, v101, v97
	v_add_f32_e32 v142, v102, v98
	v_add_f32_e32 v143, v103, v99
	v_add_f32_e32 v140, v140, v92
	v_add_f32_e32 v141, v141, v93
	v_add_f32_e32 v142, v142, v94
	v_add_f32_e32 v143, v143, v95
	v_add_f32_e32 v140, v140, v88
	v_add_f32_e32 v141, v141, v89
	v_add_f32_e32 v142, v142, v90
	v_add_f32_e32 v143, v143, v91
	v_add_f32_e32 v140, v140, v84
	v_add_f32_e32 v141, v141, v85
	v_add_f32_e32 v142, v142, v86
	v_add_f32_e32 v143, v143, v87
	v_add_f32_e32 v140, v140, v80
	v_add_f32_e32 v141, v141, v81
	v_add_f32_e32 v142, v142, v82
	v_add_f32_e32 v143, v143, v83
	v_add_f32_e32 v140, v140, v76
	v_add_f32_e32 v141, v141, v77
	v_add_f32_e32 v142, v142, v78
	v_add_f32_e32 v143, v143, v79
	v_add_f32_e32 v140, v140, v72
	v_add_f32_e32 v141, v141, v73
	v_add_f32_e32 v142, v142, v74
	v_add_f32_e32 v143, v143, v75
	v_mul_f32_e32 v140, 0x3e000000, v140
	v_mul_f32_e32 v141, 0x3e000000, v141
	v_mul_f32_e32 v142, 0x3e000000, v142
	v_mul_f32_e32 v143, 0x3e000000, v143
	v_sub_f32_e32 v140, v140, v100
	v_sub_f32_e32 v141, v141, v101
	v_sub_f32_e32 v142, v142, v102
	v_sub_f32_e32 v143, v143, v103
	v_cvt_pk_bf16_f32 v144, v140, v141
	v_cvt_pk_bf16_f32 v145, v142, v143
	global_store_dwordx2 v11, v[144:145], s[24:25]
	s_add_u32 s24, s24, 0x800
	s_addc_u32 s25, s25, 0
	s_waitcnt vmcnt(0)
	v_and_b32_e32 v107, 0xffff0000, v105
	v_lshlrev_b32_e32 v106, 16, v105
	v_and_b32_e32 v105, 0xffff0000, v104
	v_lshlrev_b32_e32 v104, 16, v104
	v_add_f32_e32 v140, v104, v100
	v_add_f32_e32 v141, v105, v101
	v_add_f32_e32 v142, v106, v102
	v_add_f32_e32 v143, v107, v103
	v_add_f32_e32 v140, v140, v96
	v_add_f32_e32 v141, v141, v97
	v_add_f32_e32 v142, v142, v98
	v_add_f32_e32 v143, v143, v99
	v_add_f32_e32 v140, v140, v92
	v_add_f32_e32 v141, v141, v93
	v_add_f32_e32 v142, v142, v94
	v_add_f32_e32 v143, v143, v95
	v_add_f32_e32 v140, v140, v88
	v_add_f32_e32 v141, v141, v89
	v_add_f32_e32 v142, v142, v90
	v_add_f32_e32 v143, v143, v91
	v_add_f32_e32 v140, v140, v84
	v_add_f32_e32 v141, v141, v85
	v_add_f32_e32 v142, v142, v86
	v_add_f32_e32 v143, v143, v87
	v_add_f32_e32 v140, v140, v80
	v_add_f32_e32 v141, v141, v81
	v_add_f32_e32 v142, v142, v82
	v_add_f32_e32 v143, v143, v83
	v_add_f32_e32 v140, v140, v76
	v_add_f32_e32 v141, v141, v77
	v_add_f32_e32 v142, v142, v78
	v_add_f32_e32 v143, v143, v79
	v_mul_f32_e32 v140, 0x3e000000, v140
	v_mul_f32_e32 v141, 0x3e000000, v141
	v_mul_f32_e32 v142, 0x3e000000, v142
	v_mul_f32_e32 v143, 0x3e000000, v143
	v_sub_f32_e32 v140, v140, v104
	v_sub_f32_e32 v141, v141, v105
	v_sub_f32_e32 v142, v142, v106
	v_sub_f32_e32 v143, v143, v107
	v_cvt_pk_bf16_f32 v144, v140, v141
	v_cvt_pk_bf16_f32 v145, v142, v143
	global_store_dwordx2 v11, v[144:145], s[24:25]
	s_add_u32 s24, s24, 0x800
	s_addc_u32 s25, s25, 0
	s_cmp_eq_u32 s18, 126
	s_cbranch_scc0 .Lp13f_next2
	s_mul_i32 s26, s17, 61440
	s_add_u32 s26, s26, 0x431c000
	s_add_u32 s22, s12, s26
	s_addc_u32 s23, s13, 0
	global_store_dwordx4 v12, v[48:51], s[22:23]
	s_add_u32 s22, s22, 0x1000
	s_addc_u32 s23, s23, 0
	global_store_dwordx4 v12, v[52:55], s[22:23]
	s_add_u32 s22, s22, 0x1000
	s_addc_u32 s23, s23, 0
	global_store_dwordx4 v12, v[56:59], s[22:23]
	s_add_u32 s22, s22, 0x1000
	s_addc_u32 s23, s23, 0
	global_store_dwordx4 v12, v[60:63], s[22:23]
	s_add_u32 s22, s22, 0x1000
	s_addc_u32 s23, s23, 0
	global_store_dwordx4 v12, v[64:67], s[22:23]
	s_add_u32 s22, s22, 0x1000
	s_addc_u32 s23, s23, 0
	global_store_dwordx4 v12, v[68:71], s[22:23]
	s_add_u32 s22, s22, 0x1000
	s_addc_u32 s23, s23, 0
	global_store_dwordx4 v12, v[72:75], s[22:23]
	s_add_u32 s22, s22, 0x1000
	s_addc_u32 s23, s23, 0
	global_store_dwordx4 v12, v[76:79], s[22:23]
	s_add_u32 s22, s22, 0x1000
	s_addc_u32 s23, s23, 0
	global_store_dwordx4 v12, v[80:83], s[22:23]
	s_add_u32 s22, s22, 0x1000
	s_addc_u32 s23, s23, 0
	global_store_dwordx4 v12, v[84:87], s[22:23]
	s_add_u32 s22, s22, 0x1000
	s_addc_u32 s23, s23, 0
	global_store_dwordx4 v12, v[88:91], s[22:23]
	s_add_u32 s22, s22, 0x1000
	s_addc_u32 s23, s23, 0
	global_store_dwordx4 v12, v[92:95], s[22:23]
	s_add_u32 s22, s22, 0x1000
	s_addc_u32 s23, s23, 0
	global_store_dwordx4 v12, v[96:99], s[22:23]
	s_add_u32 s22, s22, 0x1000
	s_addc_u32 s23, s23, 0
	global_store_dwordx4 v12, v[100:103], s[22:23]
	s_add_u32 s22, s22, 0x1000
	s_addc_u32 s23, s23, 0
	global_store_dwordx4 v12, v[104:107], s[22:23]
	s_add_u32 s22, s22, 0x1000
	s_addc_u32 s23, s23, 0

.Lp13f_w3:
	s_sub_u32 s26, s20, 15
	s_lshl_b32 s27, s26, 12
	s_lshr_b32 s28, s26, 20
	s_add_u32 s22, s8, s27
	s_addc_u32 s23, s9, s28
	global_load_dwordx2 v[16:17], v11, s[22:23]
	s_add_u32 s22, s22, 0x1000
	s_addc_u32 s23, s23, 0
	global_load_dwordx2 v[20:21], v11, s[22:23]
	s_add_u32 s22, s22, 0x1000
	s_addc_u32 s23, s23, 0
	global_load_dwordx2 v[24:25], v11, s[22:23]
	s_add_u32 s22, s22, 0x1000
	s_addc_u32 s23, s23, 0
	global_load_dwordx2 v[28:29], v11, s[22:23]
	s_add_u32 s22, s22, 0x1000
	s_addc_u32 s23, s23, 0
	global_load_dwordx2 v[32:33], v11, s[22:23]
	s_add_u32 s22, s22, 0x1000
	s_addc_u32 s23, s23, 0
	global_load_dwordx2 v[36:37], v11, s[22:23]
	s_add_u32 s22, s22, 0x1000
	s_addc_u32 s23, s23, 0
	global_load_dwordx2 v[40:41], v11, s[22:23]
	s_add_u32 s22, s22, 0x1000
	s_addc_u32 s23, s23, 0
	global_load_dwordx2 v[44:45], v11, s[22:23]
	s_add_u32 s22, s22, 0x1000
	s_addc_u32 s23, s23, 0
	global_load_dwordx2 v[48:49], v11, s[22:23]
	s_add_u32 s22, s22, 0x1000
	s_addc_u32 s23, s23, 0
	global_load_dwordx2 v[52:53], v11, s[22:23]
	s_add_u32 s22, s22, 0x1000
	s_addc_u32 s23, s23, 0
	global_load_dwordx2 v[56:57], v11, s[22:23]
	s_add_u32 s22, s22, 0x1000
	s_addc_u32 s23, s23, 0
	global_load_dwordx2 v[60:61], v11, s[22:23]
	s_add_u32 s22, s22, 0x1000
	s_addc_u32 s23, s23, 0
	global_load_dwordx2 v[64:65], v11, s[22:23]
	s_add_u32 s22, s22, 0x1000
	s_addc_u32 s23, s23, 0
	global_load_dwordx2 v[68:69], v11, s[22:23]
	s_add_u32 s22, s22, 0x1000
	s_addc_u32 s23, s23, 0
	global_load_dwordx2 v[72:73], v11, s[22:23]
	s_add_u32 s22, s22, 0x1000
	s_addc_u32 s23, s23, 0
	global_load_dwordx2 v[76:77], v11, s[22:23]
	s_add_u32 s22, s22, 0x1000
	s_addc_u32 s23, s23, 0
	global_load_dwordx2 v[80:81], v11, s[22:23]
	s_add_u32 s22, s22, 0x1000
	s_addc_u32 s23, s23, 0
	global_load_dwordx2 v[84:85], v11, s[22:23]
	s_add_u32 s22, s22, 0x1000
	s_addc_u32 s23, s23, 0
	global_load_dwordx2 v[88:89], v11, s[22:23]
	s_add_u32 s22, s22, 0x1000
	s_addc_u32 s23, s23, 0
	global_load_dwordx2 v[92:93], v11, s[22:23]
	s_add_u32 s22, s22, 0x1000
	s_addc_u32 s23, s23, 0
	global_load_dwordx2 v[96:97], v11, s[22:23]
	s_add_u32 s22, s22, 0x1000
	s_addc_u32 s23, s23, 0
	global_load_dwordx2 v[100:101], v11, s[22:23]
	s_add_u32 s22, s22, 0x1000
	s_addc_u32 s23, s23, 0
	global_load_dwordx2 v[104:105], v11, s[22:23]
	s_add_u32 s22, s22, 0x1000
	s_addc_u32 s23, s23, 0
	global_load_dwordx2 v[108:109], v11, s[22:23]
	s_add_u32 s22, s22, 0x1000
	s_addc_u32 s23, s23, 0
	global_load_dwordx2 v[112:113], v11, s[22:23]
	s_add_u32 s22, s22, 0x1000
	s_addc_u32 s23, s23, 0
	global_load_dwordx2 v[116:117], v11, s[22:23]
	s_add_u32 s22, s22, 0x1000
	s_addc_u32 s23, s23, 0
	global_load_dwordx2 v[120:121], v11, s[22:23]
	s_add_u32 s22, s22, 0x1000
	s_addc_u32 s23, s23, 0
	global_load_dwordx2 v[124:125], v11, s[22:23]
	s_add_u32 s22, s22, 0x1000
	s_addc_u32 s23, s23, 0
	global_load_dwordx2 v[128:129], v11, s[22:23]
	s_add_u32 s22, s22, 0x1000
	s_addc_u32 s23, s23, 0
	global_load_dwordx2 v[132:133], v11, s[22:23]
	s_add_u32 s22, s22, 0x1000
	s_addc_u32 s23, s23, 0
	global_load_dwordx2 v[136:137], v11, s[22:23]
	s_add_u32 s22, s22, 0x1000
	s_addc_u32 s23, s23, 0
	s_waitcnt vmcnt(15)
	v_and_b32_e32 v19, 0xffff0000, v17
	v_lshlrev_b32_e32 v18, 16, v17
	v_and_b32_e32 v17, 0xffff0000, v16
	v_lshlrev_b32_e32 v16, 16, v16
	v_and_b32_e32 v23, 0xffff0000, v21
	v_lshlrev_b32_e32 v22, 16, v21
	v_and_b32_e32 v21, 0xffff0000, v20
	v_lshlrev_b32_e32 v20, 16, v20
	v_and_b32_e32 v27, 0xffff0000, v25
	v_lshlrev_b32_e32 v26, 16, v25
	v_and_b32_e32 v25, 0xffff0000, v24
	v_lshlrev_b32_e32 v24, 16, v24
	v_and_b32_e32 v31, 0xffff0000, v29
	v_lshlrev_b32_e32 v30, 16, v29
	v_and_b32_e32 v29, 0xffff0000, v28
	v_lshlrev_b32_e32 v28, 16, v28
	v_and_b32_e32 v35, 0xffff0000, v33
	v_lshlrev_b32_e32 v34, 16, v33
	v_and_b32_e32 v33, 0xffff0000, v32
	v_lshlrev_b32_e32 v32, 16, v32
	v_and_b32_e32 v39, 0xffff0000, v37
	v_lshlrev_b32_e32 v38, 16, v37
	v_and_b32_e32 v37, 0xffff0000, v36
	v_lshlrev_b32_e32 v36, 16, v36
	v_and_b32_e32 v43, 0xffff0000, v41
	v_lshlrev_b32_e32 v42, 16, v41
	v_and_b32_e32 v41, 0xffff0000, v40
	v_lshlrev_b32_e32 v40, 16, v40
	v_and_b32_e32 v47, 0xffff0000, v45
	v_lshlrev_b32_e32 v46, 16, v45
	v_and_b32_e32 v45, 0xffff0000, v44
	v_lshlrev_b32_e32 v44, 16, v44
	v_and_b32_e32 v51, 0xffff0000, v49
	v_lshlrev_b32_e32 v50, 16, v49
	v_and_b32_e32 v49, 0xffff0000, v48
	v_lshlrev_b32_e32 v48, 16, v48
	v_and_b32_e32 v55, 0xffff0000, v53
	v_lshlrev_b32_e32 v54, 16, v53
	v_and_b32_e32 v53, 0xffff0000, v52
	v_lshlrev_b32_e32 v52, 16, v52
	v_and_b32_e32 v59, 0xffff0000, v57
	v_lshlrev_b32_e32 v58, 16, v57
	v_and_b32_e32 v57, 0xffff0000, v56
	v_lshlrev_b32_e32 v56, 16, v56
	v_and_b32_e32 v63, 0xffff0000, v61
	v_lshlrev_b32_e32 v62, 16, v61
	v_and_b32_e32 v61, 0xffff0000, v60
	v_lshlrev_b32_e32 v60, 16, v60
	v_and_b32_e32 v67, 0xffff0000, v65
	v_lshlrev_b32_e32 v66, 16, v65
	v_and_b32_e32 v65, 0xffff0000, v64
	v_lshlrev_b32_e32 v64, 16, v64
	v_and_b32_e32 v71, 0xffff0000, v69
	v_lshlrev_b32_e32 v70, 16, v69
	v_and_b32_e32 v69, 0xffff0000, v68
	v_lshlrev_b32_e32 v68, 16, v68
	v_and_b32_e32 v75, 0xffff0000, v73
	v_lshlrev_b32_e32 v74, 16, v73
	v_and_b32_e32 v73, 0xffff0000, v72
	v_lshlrev_b32_e32 v72, 16, v72
	v_and_b32_e32 v79, 0xffff0000, v77
	v_lshlrev_b32_e32 v78, 16, v77
	v_and_b32_e32 v77, 0xffff0000, v76
	v_lshlrev_b32_e32 v76, 16, v76
	v_add_f32_e32 v140, v76, v72
	v_add_f32_e32 v141, v77, v73
	v_add_f32_e32 v142, v78, v74
	v_add_f32_e32 v143, v79, v75
	v_add_f32_e32 v140, v140, v68
	v_add_f32_e32 v141, v141, v69
	v_add_f32_e32 v142, v142, v70
	v_add_f32_e32 v143, v143, v71
	v_add_f32_e32 v140, v140, v64
	v_add_f32_e32 v141, v141, v65
	v_add_f32_e32 v142, v142, v66
	v_add_f32_e32 v143, v143, v67
	v_add_f32_e32 v140, v140, v60
	v_add_f32_e32 v141, v141, v61
	v_add_f32_e32 v142, v142, v62
	v_add_f32_e32 v143, v143, v63
	v_add_f32_e32 v140, v140, v56
	v_add_f32_e32 v141, v141, v57
	v_add_f32_e32 v142, v142, v58
	v_add_f32_e32 v143, v143, v59
	v_add_f32_e32 v140, v140, v52
	v_add_f32_e32 v141, v141, v53
	v_add_f32_e32 v142, v142, v54
	v_add_f32_e32 v143, v143, v55
	v_add_f32_e32 v140, v140, v48
	v_add_f32_e32 v141, v141, v49
	v_add_f32_e32 v142, v142, v50
	v_add_f32_e32 v143, v143, v51
	v_add_f32_e32 v140, v140, v44
	v_add_f32_e32 v141, v141, v45
	v_add_f32_e32 v142, v142, v46
	v_add_f32_e32 v143, v143, v47
	v_add_f32_e32 v140, v140, v40
	v_add_f32_e32 v141, v141, v41
	v_add_f32_e32 v142, v142, v42
	v_add_f32_e32 v143, v143, v43
	v_add_f32_e32 v140, v140, v36
	v_add_f32_e32 v141, v141, v37
	v_add_f32_e32 v142, v142, v38
	v_add_f32_e32 v143, v143, v39
	v_add_f32_e32 v140, v140, v32
	v_add_f32_e32 v141, v141, v33
	v_add_f32_e32 v142, v142, v34
	v_add_f32_e32 v143, v143, v35
	v_add_f32_e32 v140, v140, v28
	v_add_f32_e32 v141, v141, v29
	v_add_f32_e32 v142, v142, v30
	v_add_f32_e32 v143, v143, v31
	v_add_f32_e32 v140, v140, v24
	v_add_f32_e32 v141, v141, v25
	v_add_f32_e32 v142, v142, v26
	v_add_f32_e32 v143, v143, v27
	v_add_f32_e32 v140, v140, v20
	v_add_f32_e32 v141, v141, v21
	v_add_f32_e32 v142, v142, v22
	v_add_f32_e32 v143, v143, v23
	v_add_f32_e32 v140, v140, v16
	v_add_f32_e32 v141, v141, v17
	v_add_f32_e32 v142, v142, v18
	v_add_f32_e32 v143, v143, v19
	v_mul_f32_e32 v140, 0x3d800000, v140
	v_mul_f32_e32 v141, 0x3d800000, v141
	v_mul_f32_e32 v142, 0x3d800000, v142
	v_mul_f32_e32 v143, 0x3d800000, v143
	v_sub_f32_e32 v140, v140, v76
	v_sub_f32_e32 v141, v141, v77
	v_sub_f32_e32 v142, v142, v78
	v_sub_f32_e32 v143, v143, v79
	v_cvt_pk_bf16_f32 v144, v140, v141
	v_cvt_pk_bf16_f32 v145, v142, v143
	global_store_dwordx2 v11, v[144:145], s[24:25]
	s_add_u32 s24, s24, 0x800
	s_addc_u32 s25, s25, 0
	s_waitcnt vmcnt(14)
	v_and_b32_e32 v83, 0xffff0000, v81
	v_lshlrev_b32_e32 v82, 16, v81
	v_and_b32_e32 v81, 0xffff0000, v80
	v_lshlrev_b32_e32 v80, 16, v80
	v_add_f32_e32 v140, v80, v76
	v_add_f32_e32 v141, v81, v77
	v_add_f32_e32 v142, v82, v78
	v_add_f32_e32 v143, v83, v79
	v_add_f32_e32 v140, v140, v72
	v_add_f32_e32 v141, v141, v73
	v_add_f32_e32 v142, v142, v74
	v_add_f32_e32 v143, v143, v75
	v_add_f32_e32 v140, v140, v68
	v_add_f32_e32 v141, v141, v69
	v_add_f32_e32 v142, v142, v70
	v_add_f32_e32 v143, v143, v71
	v_add_f32_e32 v140, v140, v64
	v_add_f32_e32 v141, v141, v65
	v_add_f32_e32 v142, v142, v66
	v_add_f32_e32 v143, v143, v67
	v_add_f32_e32 v140, v140, v60
	v_add_f32_e32 v141, v141, v61
	v_add_f32_e32 v142, v142, v62
	v_add_f32_e32 v143, v143, v63
	v_add_f32_e32 v140, v140, v56
	v_add_f32_e32 v141, v141, v57
	v_add_f32_e32 v142, v142, v58
	v_add_f32_e32 v143, v143, v59
	v_add_f32_e32 v140, v140, v52
	v_add_f32_e32 v141, v141, v53
	v_add_f32_e32 v142, v142, v54
	v_add_f32_e32 v143, v143, v55
	v_add_f32_e32 v140, v140, v48
	v_add_f32_e32 v141, v141, v49
	v_add_f32_e32 v142, v142, v50
	v_add_f32_e32 v143, v143, v51
	v_add_f32_e32 v140, v140, v44
	v_add_f32_e32 v141, v141, v45
	v_add_f32_e32 v142, v142, v46
	v_add_f32_e32 v143, v143, v47
	v_add_f32_e32 v140, v140, v40
	v_add_f32_e32 v141, v141, v41
	v_add_f32_e32 v142, v142, v42
	v_add_f32_e32 v143, v143, v43
	v_add_f32_e32 v140, v140, v36
	v_add_f32_e32 v141, v141, v37
	v_add_f32_e32 v142, v142, v38
	v_add_f32_e32 v143, v143, v39
	v_add_f32_e32 v140, v140, v32
	v_add_f32_e32 v141, v141, v33
	v_add_f32_e32 v142, v142, v34
	v_add_f32_e32 v143, v143, v35
	v_add_f32_e32 v140, v140, v28
	v_add_f32_e32 v141, v141, v29
	v_add_f32_e32 v142, v142, v30
	v_add_f32_e32 v143, v143, v31
	v_add_f32_e32 v140, v140, v24
	v_add_f32_e32 v141, v141, v25
	v_add_f32_e32 v142, v142, v26
	v_add_f32_e32 v143, v143, v27
	v_add_f32_e32 v140, v140, v20
	v_add_f32_e32 v141, v141, v21
	v_add_f32_e32 v142, v142, v22
	v_add_f32_e32 v143, v143, v23
	v_mul_f32_e32 v140, 0x3d800000, v140
	v_mul_f32_e32 v141, 0x3d800000, v141
	v_mul_f32_e32 v142, 0x3d800000, v142
	v_mul_f32_e32 v143, 0x3d800000, v143
	v_sub_f32_e32 v140, v140, v80
	v_sub_f32_e32 v141, v141, v81
	v_sub_f32_e32 v142, v142, v82
	v_sub_f32_e32 v143, v143, v83
	v_cvt_pk_bf16_f32 v144, v140, v141
	v_cvt_pk_bf16_f32 v145, v142, v143
	global_store_dwordx2 v11, v[144:145], s[24:25]
	s_add_u32 s24, s24, 0x800
	s_addc_u32 s25, s25, 0
	s_waitcnt vmcnt(13)
	v_and_b32_e32 v87, 0xffff0000, v85
	v_lshlrev_b32_e32 v86, 16, v85
	v_and_b32_e32 v85, 0xffff0000, v84
	v_lshlrev_b32_e32 v84, 16, v84
	v_add_f32_e32 v140, v84, v80
	v_add_f32_e32 v141, v85, v81
	v_add_f32_e32 v142, v86, v82
	v_add_f32_e32 v143, v87, v83
	v_add_f32_e32 v140, v140, v76
	v_add_f32_e32 v141, v141, v77
	v_add_f32_e32 v142, v142, v78
	v_add_f32_e32 v143, v143, v79
	v_add_f32_e32 v140, v140, v72
	v_add_f32_e32 v141, v141, v73
	v_add_f32_e32 v142, v142, v74
	v_add_f32_e32 v143, v143, v75
	v_add_f32_e32 v140, v140, v68
	v_add_f32_e32 v141, v141, v69
	v_add_f32_e32 v142, v142, v70
	v_add_f32_e32 v143, v143, v71
	v_add_f32_e32 v140, v140, v64
	v_add_f32_e32 v141, v141, v65
	v_add_f32_e32 v142, v142, v66
	v_add_f32_e32 v143, v143, v67
	v_add_f32_e32 v140, v140, v60
	v_add_f32_e32 v141, v141, v61
	v_add_f32_e32 v142, v142, v62
	v_add_f32_e32 v143, v143, v63
	v_add_f32_e32 v140, v140, v56
	v_add_f32_e32 v141, v141, v57
	v_add_f32_e32 v142, v142, v58
	v_add_f32_e32 v143, v143, v59
	v_add_f32_e32 v140, v140, v52
	v_add_f32_e32 v141, v141, v53
	v_add_f32_e32 v142, v142, v54
	v_add_f32_e32 v143, v143, v55
	v_add_f32_e32 v140, v140, v48
	v_add_f32_e32 v141, v141, v49
	v_add_f32_e32 v142, v142, v50
	v_add_f32_e32 v143, v143, v51
	v_add_f32_e32 v140, v140, v44
	v_add_f32_e32 v141, v141, v45
	v_add_f32_e32 v142, v142, v46
	v_add_f32_e32 v143, v143, v47
	v_add_f32_e32 v140, v140, v40
	v_add_f32_e32 v141, v141, v41
	v_add_f32_e32 v142, v142, v42
	v_add_f32_e32 v143, v143, v43
	v_add_f32_e32 v140, v140, v36
	v_add_f32_e32 v141, v141, v37
	v_add_f32_e32 v142, v142, v38
	v_add_f32_e32 v143, v143, v39
	v_add_f32_e32 v140, v140, v32
	v_add_f32_e32 v141, v141, v33
	v_add_f32_e32 v142, v142, v34
	v_add_f32_e32 v143, v143, v35
	v_add_f32_e32 v140, v140, v28
	v_add_f32_e32 v141, v141, v29
	v_add_f32_e32 v142, v142, v30
	v_add_f32_e32 v143, v143, v31
	v_add_f32_e32 v140, v140, v24
	v_add_f32_e32 v141, v141, v25
	v_add_f32_e32 v142, v142, v26
	v_add_f32_e32 v143, v143, v27
	v_mul_f32_e32 v140, 0x3d800000, v140
	v_mul_f32_e32 v141, 0x3d800000, v141
	v_mul_f32_e32 v142, 0x3d800000, v142
	v_mul_f32_e32 v143, 0x3d800000, v143
	v_sub_f32_e32 v140, v140, v84
	v_sub_f32_e32 v141, v141, v85
	v_sub_f32_e32 v142, v142, v86
	v_sub_f32_e32 v143, v143, v87
	v_cvt_pk_bf16_f32 v144, v140, v141
	v_cvt_pk_bf16_f32 v145, v142, v143
	global_store_dwordx2 v11, v[144:145], s[24:25]
	s_add_u32 s24, s24, 0x800
	s_addc_u32 s25, s25, 0
	s_waitcnt vmcnt(12)
	v_and_b32_e32 v91, 0xffff0000, v89
	v_lshlrev_b32_e32 v90, 16, v89
	v_and_b32_e32 v89, 0xffff0000, v88
	v_lshlrev_b32_e32 v88, 16, v88
	v_add_f32_e32 v140, v88, v84
	v_add_f32_e32 v141, v89, v85
	v_add_f32_e32 v142, v90, v86
	v_add_f32_e32 v143, v91, v87
	v_add_f32_e32 v140, v140, v80
	v_add_f32_e32 v141, v141, v81
	v_add_f32_e32 v142, v142, v82
	v_add_f32_e32 v143, v143, v83
	v_add_f32_e32 v140, v140, v76
	v_add_f32_e32 v141, v141, v77
	v_add_f32_e32 v142, v142, v78
	v_add_f32_e32 v143, v143, v79
	v_add_f32_e32 v140, v140, v72
	v_add_f32_e32 v141, v141, v73
	v_add_f32_e32 v142, v142, v74
	v_add_f32_e32 v143, v143, v75
	v_add_f32_e32 v140, v140, v68
	v_add_f32_e32 v141, v141, v69
	v_add_f32_e32 v142, v142, v70
	v_add_f32_e32 v143, v143, v71
	v_add_f32_e32 v140, v140, v64
	v_add_f32_e32 v141, v141, v65
	v_add_f32_e32 v142, v142, v66
	v_add_f32_e32 v143, v143, v67
	v_add_f32_e32 v140, v140, v60
	v_add_f32_e32 v141, v141, v61
	v_add_f32_e32 v142, v142, v62
	v_add_f32_e32 v143, v143, v63
	v_add_f32_e32 v140, v140, v56
	v_add_f32_e32 v141, v141, v57
	v_add_f32_e32 v142, v142, v58
	v_add_f32_e32 v143, v143, v59
	v_add_f32_e32 v140, v140, v52
	v_add_f32_e32 v141, v141, v53
	v_add_f32_e32 v142, v142, v54
	v_add_f32_e32 v143, v143, v55
	v_add_f32_e32 v140, v140, v48
	v_add_f32_e32 v141, v141, v49
	v_add_f32_e32 v142, v142, v50
	v_add_f32_e32 v143, v143, v51
	v_add_f32_e32 v140, v140, v44
	v_add_f32_e32 v141, v141, v45
	v_add_f32_e32 v142, v142, v46
	v_add_f32_e32 v143, v143, v47
	v_add_f32_e32 v140, v140, v40
	v_add_f32_e32 v141, v141, v41
	v_add_f32_e32 v142, v142, v42
	v_add_f32_e32 v143, v143, v43
	v_add_f32_e32 v140, v140, v36
	v_add_f32_e32 v141, v141, v37
	v_add_f32_e32 v142, v142, v38
	v_add_f32_e32 v143, v143, v39
	v_add_f32_e32 v140, v140, v32
	v_add_f32_e32 v141, v141, v33
	v_add_f32_e32 v142, v142, v34
	v_add_f32_e32 v143, v143, v35
	v_add_f32_e32 v140, v140, v28
	v_add_f32_e32 v141, v141, v29
	v_add_f32_e32 v142, v142, v30
	v_add_f32_e32 v143, v143, v31
	v_mul_f32_e32 v140, 0x3d800000, v140
	v_mul_f32_e32 v141, 0x3d800000, v141
	v_mul_f32_e32 v142, 0x3d800000, v142
	v_mul_f32_e32 v143, 0x3d800000, v143
	v_sub_f32_e32 v140, v140, v88
	v_sub_f32_e32 v141, v141, v89
	v_sub_f32_e32 v142, v142, v90
	v_sub_f32_e32 v143, v143, v91
	v_cvt_pk_bf16_f32 v144, v140, v141
	v_cvt_pk_bf16_f32 v145, v142, v143
	global_store_dwordx2 v11, v[144:145], s[24:25]
	s_add_u32 s24, s24, 0x800
	s_addc_u32 s25, s25, 0
	s_waitcnt vmcnt(11)
	v_and_b32_e32 v95, 0xffff0000, v93
	v_lshlrev_b32_e32 v94, 16, v93
	v_and_b32_e32 v93, 0xffff0000, v92
	v_lshlrev_b32_e32 v92, 16, v92
	v_add_f32_e32 v140, v92, v88
	v_add_f32_e32 v141, v93, v89
	v_add_f32_e32 v142, v94, v90
	v_add_f32_e32 v143, v95, v91
	v_add_f32_e32 v140, v140, v84
	v_add_f32_e32 v141, v141, v85
	v_add_f32_e32 v142, v142, v86
	v_add_f32_e32 v143, v143, v87
	v_add_f32_e32 v140, v140, v80
	v_add_f32_e32 v141, v141, v81
	v_add_f32_e32 v142, v142, v82
	v_add_f32_e32 v143, v143, v83
	v_add_f32_e32 v140, v140, v76
	v_add_f32_e32 v141, v141, v77
	v_add_f32_e32 v142, v142, v78
	v_add_f32_e32 v143, v143, v79
	v_add_f32_e32 v140, v140, v72
	v_add_f32_e32 v141, v141, v73
	v_add_f32_e32 v142, v142, v74
	v_add_f32_e32 v143, v143, v75
	v_add_f32_e32 v140, v140, v68
	v_add_f32_e32 v141, v141, v69
	v_add_f32_e32 v142, v142, v70
	v_add_f32_e32 v143, v143, v71
	v_add_f32_e32 v140, v140, v64
	v_add_f32_e32 v141, v141, v65
	v_add_f32_e32 v142, v142, v66
	v_add_f32_e32 v143, v143, v67
	v_add_f32_e32 v140, v140, v60
	v_add_f32_e32 v141, v141, v61
	v_add_f32_e32 v142, v142, v62
	v_add_f32_e32 v143, v143, v63
	v_add_f32_e32 v140, v140, v56
	v_add_f32_e32 v141, v141, v57
	v_add_f32_e32 v142, v142, v58
	v_add_f32_e32 v143, v143, v59
	v_add_f32_e32 v140, v140, v52
	v_add_f32_e32 v141, v141, v53
	v_add_f32_e32 v142, v142, v54
	v_add_f32_e32 v143, v143, v55
	v_add_f32_e32 v140, v140, v48
	v_add_f32_e32 v141, v141, v49
	v_add_f32_e32 v142, v142, v50
	v_add_f32_e32 v143, v143, v51
	v_add_f32_e32 v140, v140, v44
	v_add_f32_e32 v141, v141, v45
	v_add_f32_e32 v142, v142, v46
	v_add_f32_e32 v143, v143, v47
	v_add_f32_e32 v140, v140, v40
	v_add_f32_e32 v141, v141, v41
	v_add_f32_e32 v142, v142, v42
	v_add_f32_e32 v143, v143, v43
	v_add_f32_e32 v140, v140, v36
	v_add_f32_e32 v141, v141, v37
	v_add_f32_e32 v142, v142, v38
	v_add_f32_e32 v143, v143, v39
	v_add_f32_e32 v140, v140, v32
	v_add_f32_e32 v141, v141, v33
	v_add_f32_e32 v142, v142, v34
	v_add_f32_e32 v143, v143, v35
	v_mul_f32_e32 v140, 0x3d800000, v140
	v_mul_f32_e32 v141, 0x3d800000, v141
	v_mul_f32_e32 v142, 0x3d800000, v142
	v_mul_f32_e32 v143, 0x3d800000, v143
	v_sub_f32_e32 v140, v140, v92
	v_sub_f32_e32 v141, v141, v93
	v_sub_f32_e32 v142, v142, v94
	v_sub_f32_e32 v143, v143, v95
	v_cvt_pk_bf16_f32 v144, v140, v141
	v_cvt_pk_bf16_f32 v145, v142, v143
	global_store_dwordx2 v11, v[144:145], s[24:25]
	s_add_u32 s24, s24, 0x800
	s_addc_u32 s25, s25, 0
	s_waitcnt vmcnt(10)
	v_and_b32_e32 v99, 0xffff0000, v97
	v_lshlrev_b32_e32 v98, 16, v97
	v_and_b32_e32 v97, 0xffff0000, v96
	v_lshlrev_b32_e32 v96, 16, v96
	v_add_f32_e32 v140, v96, v92
	v_add_f32_e32 v141, v97, v93
	v_add_f32_e32 v142, v98, v94
	v_add_f32_e32 v143, v99, v95
	v_add_f32_e32 v140, v140, v88
	v_add_f32_e32 v141, v141, v89
	v_add_f32_e32 v142, v142, v90
	v_add_f32_e32 v143, v143, v91
	v_add_f32_e32 v140, v140, v84
	v_add_f32_e32 v141, v141, v85
	v_add_f32_e32 v142, v142, v86
	v_add_f32_e32 v143, v143, v87
	v_add_f32_e32 v140, v140, v80
	v_add_f32_e32 v141, v141, v81
	v_add_f32_e32 v142, v142, v82
	v_add_f32_e32 v143, v143, v83
	v_add_f32_e32 v140, v140, v76
	v_add_f32_e32 v141, v141, v77
	v_add_f32_e32 v142, v142, v78
	v_add_f32_e32 v143, v143, v79
	v_add_f32_e32 v140, v140, v72
	v_add_f32_e32 v141, v141, v73
	v_add_f32_e32 v142, v142, v74
	v_add_f32_e32 v143, v143, v75
	v_add_f32_e32 v140, v140, v68
	v_add_f32_e32 v141, v141, v69
	v_add_f32_e32 v142, v142, v70
	v_add_f32_e32 v143, v143, v71
	v_add_f32_e32 v140, v140, v64
	v_add_f32_e32 v141, v141, v65
	v_add_f32_e32 v142, v142, v66
	v_add_f32_e32 v143, v143, v67
	v_add_f32_e32 v140, v140, v60
	v_add_f32_e32 v141, v141, v61
	v_add_f32_e32 v142, v142, v62
	v_add_f32_e32 v143, v143, v63
	v_add_f32_e32 v140, v140, v56
	v_add_f32_e32 v141, v141, v57
	v_add_f32_e32 v142, v142, v58
	v_add_f32_e32 v143, v143, v59
	v_add_f32_e32 v140, v140, v52
	v_add_f32_e32 v141, v141, v53
	v_add_f32_e32 v142, v142, v54
	v_add_f32_e32 v143, v143, v55
	v_add_f32_e32 v140, v140, v48
	v_add_f32_e32 v141, v141, v49
	v_add_f32_e32 v142, v142, v50
	v_add_f32_e32 v143, v143, v51
	v_add_f32_e32 v140, v140, v44
	v_add_f32_e32 v141, v141, v45
	v_add_f32_e32 v142, v142, v46
	v_add_f32_e32 v143, v143, v47
	v_add_f32_e32 v140, v140, v40
	v_add_f32_e32 v141, v141, v41
	v_add_f32_e32 v142, v142, v42
	v_add_f32_e32 v143, v143, v43
	v_add_f32_e32 v140, v140, v36
	v_add_f32_e32 v141, v141, v37
	v_add_f32_e32 v142, v142, v38
	v_add_f32_e32 v143, v143, v39
	v_mul_f32_e32 v140, 0x3d800000, v140
	v_mul_f32_e32 v141, 0x3d800000, v141
	v_mul_f32_e32 v142, 0x3d800000, v142
	v_mul_f32_e32 v143, 0x3d800000, v143
	v_sub_f32_e32 v140, v140, v96
	v_sub_f32_e32 v141, v141, v97
	v_sub_f32_e32 v142, v142, v98
	v_sub_f32_e32 v143, v143, v99
	v_cvt_pk_bf16_f32 v144, v140, v141
	v_cvt_pk_bf16_f32 v145, v142, v143
	global_store_dwordx2 v11, v[144:145], s[24:25]
	s_add_u32 s24, s24, 0x800
	s_addc_u32 s25, s25, 0
	s_waitcnt vmcnt(9)
	v_and_b32_e32 v103, 0xffff0000, v101
	v_lshlrev_b32_e32 v102, 16, v101
	v_and_b32_e32 v101, 0xffff0000, v100
	v_lshlrev_b32_e32 v100, 16, v100
	v_add_f32_e32 v140, v100, v96
	v_add_f32_e32 v141, v101, v97
	v_add_f32_e32 v142, v102, v98
	v_add_f32_e32 v143, v103, v99
	v_add_f32_e32 v140, v140, v92
	v_add_f32_e32 v141, v141, v93
	v_add_f32_e32 v142, v142, v94
	v_add_f32_e32 v143, v143, v95
	v_add_f32_e32 v140, v140, v88
	v_add_f32_e32 v141, v141, v89
	v_add_f32_e32 v142, v142, v90
	v_add_f32_e32 v143, v143, v91
	v_add_f32_e32 v140, v140, v84
	v_add_f32_e32 v141, v141, v85
	v_add_f32_e32 v142, v142, v86
	v_add_f32_e32 v143, v143, v87
	v_add_f32_e32 v140, v140, v80
	v_add_f32_e32 v141, v141, v81
	v_add_f32_e32 v142, v142, v82
	v_add_f32_e32 v143, v143, v83
	v_add_f32_e32 v140, v140, v76
	v_add_f32_e32 v141, v141, v77
	v_add_f32_e32 v142, v142, v78
	v_add_f32_e32 v143, v143, v79
	v_add_f32_e32 v140, v140, v72
	v_add_f32_e32 v141, v141, v73
	v_add_f32_e32 v142, v142, v74
	v_add_f32_e32 v143, v143, v75
	v_add_f32_e32 v140, v140, v68
	v_add_f32_e32 v141, v141, v69
	v_add_f32_e32 v142, v142, v70
	v_add_f32_e32 v143, v143, v71
	v_add_f32_e32 v140, v140, v64
	v_add_f32_e32 v141, v141, v65
	v_add_f32_e32 v142, v142, v66
	v_add_f32_e32 v143, v143, v67
	v_add_f32_e32 v140, v140, v60
	v_add_f32_e32 v141, v141, v61
	v_add_f32_e32 v142, v142, v62
	v_add_f32_e32 v143, v143, v63
	v_add_f32_e32 v140, v140, v56
	v_add_f32_e32 v141, v141, v57
	v_add_f32_e32 v142, v142, v58
	v_add_f32_e32 v143, v143, v59
	v_add_f32_e32 v140, v140, v52
	v_add_f32_e32 v141, v141, v53
	v_add_f32_e32 v142, v142, v54
	v_add_f32_e32 v143, v143, v55
	v_add_f32_e32 v140, v140, v48
	v_add_f32_e32 v141, v141, v49
	v_add_f32_e32 v142, v142, v50
	v_add_f32_e32 v143, v143, v51
	v_add_f32_e32 v140, v140, v44
	v_add_f32_e32 v141, v141, v45
	v_add_f32_e32 v142, v142, v46
	v_add_f32_e32 v143, v143, v47
	v_add_f32_e32 v140, v140, v40
	v_add_f32_e32 v141, v141, v41
	v_add_f32_e32 v142, v142, v42
	v_add_f32_e32 v143, v143, v43
	v_mul_f32_e32 v140, 0x3d800000, v140
	v_mul_f32_e32 v141, 0x3d800000, v141
	v_mul_f32_e32 v142, 0x3d800000, v142
	v_mul_f32_e32 v143, 0x3d800000, v143
	v_sub_f32_e32 v140, v140, v100
	v_sub_f32_e32 v141, v141, v101
	v_sub_f32_e32 v142, v142, v102
	v_sub_f32_e32 v143, v143, v103
	v_cvt_pk_bf16_f32 v144, v140, v141
	v_cvt_pk_bf16_f32 v145, v142, v143
	global_store_dwordx2 v11, v[144:145], s[24:25]
	s_add_u32 s24, s24, 0x800
	s_addc_u32 s25, s25, 0
	s_waitcnt vmcnt(8)
	v_and_b32_e32 v107, 0xffff0000, v105
	v_lshlrev_b32_e32 v106, 16, v105
	v_and_b32_e32 v105, 0xffff0000, v104
	v_lshlrev_b32_e32 v104, 16, v104
	v_add_f32_e32 v140, v104, v100
	v_add_f32_e32 v141, v105, v101
	v_add_f32_e32 v142, v106, v102
	v_add_f32_e32 v143, v107, v103
	v_add_f32_e32 v140, v140, v96
	v_add_f32_e32 v141, v141, v97
	v_add_f32_e32 v142, v142, v98
	v_add_f32_e32 v143, v143, v99
	v_add_f32_e32 v140, v140, v92
	v_add_f32_e32 v141, v141, v93
	v_add_f32_e32 v142, v142, v94
	v_add_f32_e32 v143, v143, v95
	v_add_f32_e32 v140, v140, v88
	v_add_f32_e32 v141, v141, v89
	v_add_f32_e32 v142, v142, v90
	v_add_f32_e32 v143, v143, v91
	v_add_f32_e32 v140, v140, v84
	v_add_f32_e32 v141, v141, v85
	v_add_f32_e32 v142, v142, v86
	v_add_f32_e32 v143, v143, v87
	v_add_f32_e32 v140, v140, v80
	v_add_f32_e32 v141, v141, v81
	v_add_f32_e32 v142, v142, v82
	v_add_f32_e32 v143, v143, v83
	v_add_f32_e32 v140, v140, v76
	v_add_f32_e32 v141, v141, v77
	v_add_f32_e32 v142, v142, v78
	v_add_f32_e32 v143, v143, v79
	v_add_f32_e32 v140, v140, v72
	v_add_f32_e32 v141, v141, v73
	v_add_f32_e32 v142, v142, v74
	v_add_f32_e32 v143, v143, v75
	v_add_f32_e32 v140, v140, v68
	v_add_f32_e32 v141, v141, v69
	v_add_f32_e32 v142, v142, v70
	v_add_f32_e32 v143, v143, v71
	v_add_f32_e32 v140, v140, v64
	v_add_f32_e32 v141, v141, v65
	v_add_f32_e32 v142, v142, v66
	v_add_f32_e32 v143, v143, v67
	v_add_f32_e32 v140, v140, v60
	v_add_f32_e32 v141, v141, v61
	v_add_f32_e32 v142, v142, v62
	v_add_f32_e32 v143, v143, v63
	v_add_f32_e32 v140, v140, v56
	v_add_f32_e32 v141, v141, v57
	v_add_f32_e32 v142, v142, v58
	v_add_f32_e32 v143, v143, v59
	v_add_f32_e32 v140, v140, v52
	v_add_f32_e32 v141, v141, v53
	v_add_f32_e32 v142, v142, v54
	v_add_f32_e32 v143, v143, v55
	v_add_f32_e32 v140, v140, v48
	v_add_f32_e32 v141, v141, v49
	v_add_f32_e32 v142, v142, v50
	v_add_f32_e32 v143, v143, v51
	v_add_f32_e32 v140, v140, v44
	v_add_f32_e32 v141, v141, v45
	v_add_f32_e32 v142, v142, v46
	v_add_f32_e32 v143, v143, v47
	v_mul_f32_e32 v140, 0x3d800000, v140
	v_mul_f32_e32 v141, 0x3d800000, v141
	v_mul_f32_e32 v142, 0x3d800000, v142
	v_mul_f32_e32 v143, 0x3d800000, v143
	v_sub_f32_e32 v140, v140, v104
	v_sub_f32_e32 v141, v141, v105
	v_sub_f32_e32 v142, v142, v106
	v_sub_f32_e32 v143, v143, v107
	v_cvt_pk_bf16_f32 v144, v140, v141
	v_cvt_pk_bf16_f32 v145, v142, v143
	global_store_dwordx2 v11, v[144:145], s[24:25]
	s_add_u32 s24, s24, 0x800
	s_addc_u32 s25, s25, 0
	s_waitcnt vmcnt(7)
	v_and_b32_e32 v111, 0xffff0000, v109
	v_lshlrev_b32_e32 v110, 16, v109
	v_and_b32_e32 v109, 0xffff0000, v108
	v_lshlrev_b32_e32 v108, 16, v108
	v_add_f32_e32 v140, v108, v104
	v_add_f32_e32 v141, v109, v105
	v_add_f32_e32 v142, v110, v106
	v_add_f32_e32 v143, v111, v107
	v_add_f32_e32 v140, v140, v100
	v_add_f32_e32 v141, v141, v101
	v_add_f32_e32 v142, v142, v102
	v_add_f32_e32 v143, v143, v103
	v_add_f32_e32 v140, v140, v96
	v_add_f32_e32 v141, v141, v97
	v_add_f32_e32 v142, v142, v98
	v_add_f32_e32 v143, v143, v99
	v_add_f32_e32 v140, v140, v92
	v_add_f32_e32 v141, v141, v93
	v_add_f32_e32 v142, v142, v94
	v_add_f32_e32 v143, v143, v95
	v_add_f32_e32 v140, v140, v88
	v_add_f32_e32 v141, v141, v89
	v_add_f32_e32 v142, v142, v90
	v_add_f32_e32 v143, v143, v91
	v_add_f32_e32 v140, v140, v84
	v_add_f32_e32 v141, v141, v85
	v_add_f32_e32 v142, v142, v86
	v_add_f32_e32 v143, v143, v87
	v_add_f32_e32 v140, v140, v80
	v_add_f32_e32 v141, v141, v81
	v_add_f32_e32 v142, v142, v82
	v_add_f32_e32 v143, v143, v83
	v_add_f32_e32 v140, v140, v76
	v_add_f32_e32 v141, v141, v77
	v_add_f32_e32 v142, v142, v78
	v_add_f32_e32 v143, v143, v79
	v_add_f32_e32 v140, v140, v72
	v_add_f32_e32 v141, v141, v73
	v_add_f32_e32 v142, v142, v74
	v_add_f32_e32 v143, v143, v75
	v_add_f32_e32 v140, v140, v68
	v_add_f32_e32 v141, v141, v69
	v_add_f32_e32 v142, v142, v70
	v_add_f32_e32 v143, v143, v71
	v_add_f32_e32 v140, v140, v64
	v_add_f32_e32 v141, v141, v65
	v_add_f32_e32 v142, v142, v66
	v_add_f32_e32 v143, v143, v67
	v_add_f32_e32 v140, v140, v60
	v_add_f32_e32 v141, v141, v61
	v_add_f32_e32 v142, v142, v62
	v_add_f32_e32 v143, v143, v63
	v_add_f32_e32 v140, v140, v56
	v_add_f32_e32 v141, v141, v57
	v_add_f32_e32 v142, v142, v58
	v_add_f32_e32 v143, v143, v59
	v_add_f32_e32 v140, v140, v52
	v_add_f32_e32 v141, v141, v53
	v_add_f32_e32 v142, v142, v54
	v_add_f32_e32 v143, v143, v55
	v_add_f32_e32 v140, v140, v48
	v_add_f32_e32 v141, v141, v49
	v_add_f32_e32 v142, v142, v50
	v_add_f32_e32 v143, v143, v51
	v_mul_f32_e32 v140, 0x3d800000, v140
	v_mul_f32_e32 v141, 0x3d800000, v141
	v_mul_f32_e32 v142, 0x3d800000, v142
	v_mul_f32_e32 v143, 0x3d800000, v143
	v_sub_f32_e32 v140, v140, v108
	v_sub_f32_e32 v141, v141, v109
	v_sub_f32_e32 v142, v142, v110
	v_sub_f32_e32 v143, v143, v111
	v_cvt_pk_bf16_f32 v144, v140, v141
	v_cvt_pk_bf16_f32 v145, v142, v143
	global_store_dwordx2 v11, v[144:145], s[24:25]
	s_add_u32 s24, s24, 0x800
	s_addc_u32 s25, s25, 0
	s_waitcnt vmcnt(6)
	v_and_b32_e32 v115, 0xffff0000, v113
	v_lshlrev_b32_e32 v114, 16, v113
	v_and_b32_e32 v113, 0xffff0000, v112
	v_lshlrev_b32_e32 v112, 16, v112
	v_add_f32_e32 v140, v112, v108
	v_add_f32_e32 v141, v113, v109
	v_add_f32_e32 v142, v114, v110
	v_add_f32_e32 v143, v115, v111
	v_add_f32_e32 v140, v140, v104
	v_add_f32_e32 v141, v141, v105
	v_add_f32_e32 v142, v142, v106
	v_add_f32_e32 v143, v143, v107
	v_add_f32_e32 v140, v140, v100
	v_add_f32_e32 v141, v141, v101
	v_add_f32_e32 v142, v142, v102
	v_add_f32_e32 v143, v143, v103
	v_add_f32_e32 v140, v140, v96
	v_add_f32_e32 v141, v141, v97
	v_add_f32_e32 v142, v142, v98
	v_add_f32_e32 v143, v143, v99
	v_add_f32_e32 v140, v140, v92
	v_add_f32_e32 v141, v141, v93
	v_add_f32_e32 v142, v142, v94
	v_add_f32_e32 v143, v143, v95
	v_add_f32_e32 v140, v140, v88
	v_add_f32_e32 v141, v141, v89
	v_add_f32_e32 v142, v142, v90
	v_add_f32_e32 v143, v143, v91
	v_add_f32_e32 v140, v140, v84
	v_add_f32_e32 v141, v141, v85
	v_add_f32_e32 v142, v142, v86
	v_add_f32_e32 v143, v143, v87
	v_add_f32_e32 v140, v140, v80
	v_add_f32_e32 v141, v141, v81
	v_add_f32_e32 v142, v142, v82
	v_add_f32_e32 v143, v143, v83
	v_add_f32_e32 v140, v140, v76
	v_add_f32_e32 v141, v141, v77
	v_add_f32_e32 v142, v142, v78
	v_add_f32_e32 v143, v143, v79
	v_add_f32_e32 v140, v140, v72
	v_add_f32_e32 v141, v141, v73
	v_add_f32_e32 v142, v142, v74
	v_add_f32_e32 v143, v143, v75
	v_add_f32_e32 v140, v140, v68
	v_add_f32_e32 v141, v141, v69
	v_add_f32_e32 v142, v142, v70
	v_add_f32_e32 v143, v143, v71
	v_add_f32_e32 v140, v140, v64
	v_add_f32_e32 v141, v141, v65
	v_add_f32_e32 v142, v142, v66
	v_add_f32_e32 v143, v143, v67
	v_add_f32_e32 v140, v140, v60
	v_add_f32_e32 v141, v141, v61
	v_add_f32_e32 v142, v142, v62
	v_add_f32_e32 v143, v143, v63
	v_add_f32_e32 v140, v140, v56
	v_add_f32_e32 v141, v141, v57
	v_add_f32_e32 v142, v142, v58
	v_add_f32_e32 v143, v143, v59
	v_add_f32_e32 v140, v140, v52
	v_add_f32_e32 v141, v141, v53
	v_add_f32_e32 v142, v142, v54
	v_add_f32_e32 v143, v143, v55
	v_mul_f32_e32 v140, 0x3d800000, v140
	v_mul_f32_e32 v141, 0x3d800000, v141
	v_mul_f32_e32 v142, 0x3d800000, v142
	v_mul_f32_e32 v143, 0x3d800000, v143
	v_sub_f32_e32 v140, v140, v112
	v_sub_f32_e32 v141, v141, v113
	v_sub_f32_e32 v142, v142, v114
	v_sub_f32_e32 v143, v143, v115
	v_cvt_pk_bf16_f32 v144, v140, v141
	v_cvt_pk_bf16_f32 v145, v142, v143
	global_store_dwordx2 v11, v[144:145], s[24:25]
	s_add_u32 s24, s24, 0x800
	s_addc_u32 s25, s25, 0
	s_waitcnt vmcnt(5)
	v_and_b32_e32 v119, 0xffff0000, v117
	v_lshlrev_b32_e32 v118, 16, v117
	v_and_b32_e32 v117, 0xffff0000, v116
	v_lshlrev_b32_e32 v116, 16, v116
	v_add_f32_e32 v140, v116, v112
	v_add_f32_e32 v141, v117, v113
	v_add_f32_e32 v142, v118, v114
	v_add_f32_e32 v143, v119, v115
	v_add_f32_e32 v140, v140, v108
	v_add_f32_e32 v141, v141, v109
	v_add_f32_e32 v142, v142, v110
	v_add_f32_e32 v143, v143, v111
	v_add_f32_e32 v140, v140, v104
	v_add_f32_e32 v141, v141, v105
	v_add_f32_e32 v142, v142, v106
	v_add_f32_e32 v143, v143, v107
	v_add_f32_e32 v140, v140, v100
	v_add_f32_e32 v141, v141, v101
	v_add_f32_e32 v142, v142, v102
	v_add_f32_e32 v143, v143, v103
	v_add_f32_e32 v140, v140, v96
	v_add_f32_e32 v141, v141, v97
	v_add_f32_e32 v142, v142, v98
	v_add_f32_e32 v143, v143, v99
	v_add_f32_e32 v140, v140, v92
	v_add_f32_e32 v141, v141, v93
	v_add_f32_e32 v142, v142, v94
	v_add_f32_e32 v143, v143, v95
	v_add_f32_e32 v140, v140, v88
	v_add_f32_e32 v141, v141, v89
	v_add_f32_e32 v142, v142, v90
	v_add_f32_e32 v143, v143, v91
	v_add_f32_e32 v140, v140, v84
	v_add_f32_e32 v141, v141, v85
	v_add_f32_e32 v142, v142, v86
	v_add_f32_e32 v143, v143, v87
	v_add_f32_e32 v140, v140, v80
	v_add_f32_e32 v141, v141, v81
	v_add_f32_e32 v142, v142, v82
	v_add_f32_e32 v143, v143, v83
	v_add_f32_e32 v140, v140, v76
	v_add_f32_e32 v141, v141, v77
	v_add_f32_e32 v142, v142, v78
	v_add_f32_e32 v143, v143, v79
	v_add_f32_e32 v140, v140, v72
	v_add_f32_e32 v141, v141, v73
	v_add_f32_e32 v142, v142, v74
	v_add_f32_e32 v143, v143, v75
	v_add_f32_e32 v140, v140, v68
	v_add_f32_e32 v141, v141, v69
	v_add_f32_e32 v142, v142, v70
	v_add_f32_e32 v143, v143, v71
	v_add_f32_e32 v140, v140, v64
	v_add_f32_e32 v141, v141, v65
	v_add_f32_e32 v142, v142, v66
	v_add_f32_e32 v143, v143, v67
	v_add_f32_e32 v140, v140, v60
	v_add_f32_e32 v141, v141, v61
	v_add_f32_e32 v142, v142, v62
	v_add_f32_e32 v143, v143, v63
	v_add_f32_e32 v140, v140, v56
	v_add_f32_e32 v141, v141, v57
	v_add_f32_e32 v142, v142, v58
	v_add_f32_e32 v143, v143, v59
	v_mul_f32_e32 v140, 0x3d800000, v140
	v_mul_f32_e32 v141, 0x3d800000, v141
	v_mul_f32_e32 v142, 0x3d800000, v142
	v_mul_f32_e32 v143, 0x3d800000, v143
	v_sub_f32_e32 v140, v140, v116
	v_sub_f32_e32 v141, v141, v117
	v_sub_f32_e32 v142, v142, v118
	v_sub_f32_e32 v143, v143, v119
	v_cvt_pk_bf16_f32 v144, v140, v141
	v_cvt_pk_bf16_f32 v145, v142, v143
	global_store_dwordx2 v11, v[144:145], s[24:25]
	s_add_u32 s24, s24, 0x800
	s_addc_u32 s25, s25, 0
	s_waitcnt vmcnt(4)
	v_and_b32_e32 v123, 0xffff0000, v121
	v_lshlrev_b32_e32 v122, 16, v121
	v_and_b32_e32 v121, 0xffff0000, v120
	v_lshlrev_b32_e32 v120, 16, v120
	v_add_f32_e32 v140, v120, v116
	v_add_f32_e32 v141, v121, v117
	v_add_f32_e32 v142, v122, v118
	v_add_f32_e32 v143, v123, v119
	v_add_f32_e32 v140, v140, v112
	v_add_f32_e32 v141, v141, v113
	v_add_f32_e32 v142, v142, v114
	v_add_f32_e32 v143, v143, v115
	v_add_f32_e32 v140, v140, v108
	v_add_f32_e32 v141, v141, v109
	v_add_f32_e32 v142, v142, v110
	v_add_f32_e32 v143, v143, v111
	v_add_f32_e32 v140, v140, v104
	v_add_f32_e32 v141, v141, v105
	v_add_f32_e32 v142, v142, v106
	v_add_f32_e32 v143, v143, v107
	v_add_f32_e32 v140, v140, v100
	v_add_f32_e32 v141, v141, v101
	v_add_f32_e32 v142, v142, v102
	v_add_f32_e32 v143, v143, v103
	v_add_f32_e32 v140, v140, v96
	v_add_f32_e32 v141, v141, v97
	v_add_f32_e32 v142, v142, v98
	v_add_f32_e32 v143, v143, v99
	v_add_f32_e32 v140, v140, v92
	v_add_f32_e32 v141, v141, v93
	v_add_f32_e32 v142, v142, v94
	v_add_f32_e32 v143, v143, v95
	v_add_f32_e32 v140, v140, v88
	v_add_f32_e32 v141, v141, v89
	v_add_f32_e32 v142, v142, v90
	v_add_f32_e32 v143, v143, v91
	v_add_f32_e32 v140, v140, v84
	v_add_f32_e32 v141, v141, v85
	v_add_f32_e32 v142, v142, v86
	v_add_f32_e32 v143, v143, v87
	v_add_f32_e32 v140, v140, v80
	v_add_f32_e32 v141, v141, v81
	v_add_f32_e32 v142, v142, v82
	v_add_f32_e32 v143, v143, v83
	v_add_f32_e32 v140, v140, v76
	v_add_f32_e32 v141, v141, v77
	v_add_f32_e32 v142, v142, v78
	v_add_f32_e32 v143, v143, v79
	v_add_f32_e32 v140, v140, v72
	v_add_f32_e32 v141, v141, v73
	v_add_f32_e32 v142, v142, v74
	v_add_f32_e32 v143, v143, v75
	v_add_f32_e32 v140, v140, v68
	v_add_f32_e32 v141, v141, v69
	v_add_f32_e32 v142, v142, v70
	v_add_f32_e32 v143, v143, v71
	v_add_f32_e32 v140, v140, v64
	v_add_f32_e32 v141, v141, v65
	v_add_f32_e32 v142, v142, v66
	v_add_f32_e32 v143, v143, v67
	v_add_f32_e32 v140, v140, v60
	v_add_f32_e32 v141, v141, v61
	v_add_f32_e32 v142, v142, v62
	v_add_f32_e32 v143, v143, v63
	v_mul_f32_e32 v140, 0x3d800000, v140
	v_mul_f32_e32 v141, 0x3d800000, v141
	v_mul_f32_e32 v142, 0x3d800000, v142
	v_mul_f32_e32 v143, 0x3d800000, v143
	v_sub_f32_e32 v140, v140, v120
	v_sub_f32_e32 v141, v141, v121
	v_sub_f32_e32 v142, v142, v122
	v_sub_f32_e32 v143, v143, v123
	v_cvt_pk_bf16_f32 v144, v140, v141
	v_cvt_pk_bf16_f32 v145, v142, v143
	global_store_dwordx2 v11, v[144:145], s[24:25]
	s_add_u32 s24, s24, 0x800
	s_addc_u32 s25, s25, 0
	s_waitcnt vmcnt(3)
	v_and_b32_e32 v127, 0xffff0000, v125
	v_lshlrev_b32_e32 v126, 16, v125
	v_and_b32_e32 v125, 0xffff0000, v124
	v_lshlrev_b32_e32 v124, 16, v124
	v_add_f32_e32 v140, v124, v120
	v_add_f32_e32 v141, v125, v121
	v_add_f32_e32 v142, v126, v122
	v_add_f32_e32 v143, v127, v123
	v_add_f32_e32 v140, v140, v116
	v_add_f32_e32 v141, v141, v117
	v_add_f32_e32 v142, v142, v118
	v_add_f32_e32 v143, v143, v119
	v_add_f32_e32 v140, v140, v112
	v_add_f32_e32 v141, v141, v113
	v_add_f32_e32 v142, v142, v114
	v_add_f32_e32 v143, v143, v115
	v_add_f32_e32 v140, v140, v108
	v_add_f32_e32 v141, v141, v109
	v_add_f32_e32 v142, v142, v110
	v_add_f32_e32 v143, v143, v111
	v_add_f32_e32 v140, v140, v104
	v_add_f32_e32 v141, v141, v105
	v_add_f32_e32 v142, v142, v106
	v_add_f32_e32 v143, v143, v107
	v_add_f32_e32 v140, v140, v100
	v_add_f32_e32 v141, v141, v101
	v_add_f32_e32 v142, v142, v102
	v_add_f32_e32 v143, v143, v103
	v_add_f32_e32 v140, v140, v96
	v_add_f32_e32 v141, v141, v97
	v_add_f32_e32 v142, v142, v98
	v_add_f32_e32 v143, v143, v99
	v_add_f32_e32 v140, v140, v92
	v_add_f32_e32 v141, v141, v93
	v_add_f32_e32 v142, v142, v94
	v_add_f32_e32 v143, v143, v95
	v_add_f32_e32 v140, v140, v88
	v_add_f32_e32 v141, v141, v89
	v_add_f32_e32 v142, v142, v90
	v_add_f32_e32 v143, v143, v91
	v_add_f32_e32 v140, v140, v84
	v_add_f32_e32 v141, v141, v85
	v_add_f32_e32 v142, v142, v86
	v_add_f32_e32 v143, v143, v87
	v_add_f32_e32 v140, v140, v80
	v_add_f32_e32 v141, v141, v81
	v_add_f32_e32 v142, v142, v82
	v_add_f32_e32 v143, v143, v83
	v_add_f32_e32 v140, v140, v76
	v_add_f32_e32 v141, v141, v77
	v_add_f32_e32 v142, v142, v78
	v_add_f32_e32 v143, v143, v79
	v_add_f32_e32 v140, v140, v72
	v_add_f32_e32 v141, v141, v73
	v_add_f32_e32 v142, v142, v74
	v_add_f32_e32 v143, v143, v75
	v_add_f32_e32 v140, v140, v68
	v_add_f32_e32 v141, v141, v69
	v_add_f32_e32 v142, v142, v70
	v_add_f32_e32 v143, v143, v71
	v_add_f32_e32 v140, v140, v64
	v_add_f32_e32 v141, v141, v65
	v_add_f32_e32 v142, v142, v66
	v_add_f32_e32 v143, v143, v67
	v_mul_f32_e32 v140, 0x3d800000, v140
	v_mul_f32_e32 v141, 0x3d800000, v141
	v_mul_f32_e32 v142, 0x3d800000, v142
	v_mul_f32_e32 v143, 0x3d800000, v143
	v_sub_f32_e32 v140, v140, v124
	v_sub_f32_e32 v141, v141, v125
	v_sub_f32_e32 v142, v142, v126
	v_sub_f32_e32 v143, v143, v127
	v_cvt_pk_bf16_f32 v144, v140, v141
	v_cvt_pk_bf16_f32 v145, v142, v143
	global_store_dwordx2 v11, v[144:145], s[24:25]
	s_add_u32 s24, s24, 0x800
	s_addc_u32 s25, s25, 0
	s_waitcnt vmcnt(2)
	v_and_b32_e32 v131, 0xffff0000, v129
	v_lshlrev_b32_e32 v130, 16, v129
	v_and_b32_e32 v129, 0xffff0000, v128
	v_lshlrev_b32_e32 v128, 16, v128
	v_add_f32_e32 v140, v128, v124
	v_add_f32_e32 v141, v129, v125
	v_add_f32_e32 v142, v130, v126
	v_add_f32_e32 v143, v131, v127
	v_add_f32_e32 v140, v140, v120
	v_add_f32_e32 v141, v141, v121
	v_add_f32_e32 v142, v142, v122
	v_add_f32_e32 v143, v143, v123
	v_add_f32_e32 v140, v140, v116
	v_add_f32_e32 v141, v141, v117
	v_add_f32_e32 v142, v142, v118
	v_add_f32_e32 v143, v143, v119
	v_add_f32_e32 v140, v140, v112
	v_add_f32_e32 v141, v141, v113
	v_add_f32_e32 v142, v142, v114
	v_add_f32_e32 v143, v143, v115
	v_add_f32_e32 v140, v140, v108
	v_add_f32_e32 v141, v141, v109
	v_add_f32_e32 v142, v142, v110
	v_add_f32_e32 v143, v143, v111
	v_add_f32_e32 v140, v140, v104
	v_add_f32_e32 v141, v141, v105
	v_add_f32_e32 v142, v142, v106
	v_add_f32_e32 v143, v143, v107
	v_add_f32_e32 v140, v140, v100
	v_add_f32_e32 v141, v141, v101
	v_add_f32_e32 v142, v142, v102
	v_add_f32_e32 v143, v143, v103
	v_add_f32_e32 v140, v140, v96
	v_add_f32_e32 v141, v141, v97
	v_add_f32_e32 v142, v142, v98
	v_add_f32_e32 v143, v143, v99
	v_add_f32_e32 v140, v140, v92
	v_add_f32_e32 v141, v141, v93
	v_add_f32_e32 v142, v142, v94
	v_add_f32_e32 v143, v143, v95
	v_add_f32_e32 v140, v140, v88
	v_add_f32_e32 v141, v141, v89
	v_add_f32_e32 v142, v142, v90
	v_add_f32_e32 v143, v143, v91
	v_add_f32_e32 v140, v140, v84
	v_add_f32_e32 v141, v141, v85
	v_add_f32_e32 v142, v142, v86
	v_add_f32_e32 v143, v143, v87
	v_add_f32_e32 v140, v140, v80
	v_add_f32_e32 v141, v141, v81
	v_add_f32_e32 v142, v142, v82
	v_add_f32_e32 v143, v143, v83
	v_add_f32_e32 v140, v140, v76
	v_add_f32_e32 v141, v141, v77
	v_add_f32_e32 v142, v142, v78
	v_add_f32_e32 v143, v143, v79
	v_add_f32_e32 v140, v140, v72
	v_add_f32_e32 v141, v141, v73
	v_add_f32_e32 v142, v142, v74
	v_add_f32_e32 v143, v143, v75
	v_add_f32_e32 v140, v140, v68
	v_add_f32_e32 v141, v141, v69
	v_add_f32_e32 v142, v142, v70
	v_add_f32_e32 v143, v143, v71
	v_mul_f32_e32 v140, 0x3d800000, v140
	v_mul_f32_e32 v141, 0x3d800000, v141
	v_mul_f32_e32 v142, 0x3d800000, v142
	v_mul_f32_e32 v143, 0x3d800000, v143
	v_sub_f32_e32 v140, v140, v128
	v_sub_f32_e32 v141, v141, v129
	v_sub_f32_e32 v142, v142, v130
	v_sub_f32_e32 v143, v143, v131
	v_cvt_pk_bf16_f32 v144, v140, v141
	v_cvt_pk_bf16_f32 v145, v142, v143
	global_store_dwordx2 v11, v[144:145], s[24:25]
	s_add_u32 s24, s24, 0x800
	s_addc_u32 s25, s25, 0
	s_waitcnt vmcnt(1)
	v_and_b32_e32 v135, 0xffff0000, v133
	v_lshlrev_b32_e32 v134, 16, v133
	v_and_b32_e32 v133, 0xffff0000, v132
	v_lshlrev_b32_e32 v132, 16, v132
	v_add_f32_e32 v140, v132, v128
	v_add_f32_e32 v141, v133, v129
	v_add_f32_e32 v142, v134, v130
	v_add_f32_e32 v143, v135, v131
	v_add_f32_e32 v140, v140, v124
	v_add_f32_e32 v141, v141, v125
	v_add_f32_e32 v142, v142, v126
	v_add_f32_e32 v143, v143, v127
	v_add_f32_e32 v140, v140, v120
	v_add_f32_e32 v141, v141, v121
	v_add_f32_e32 v142, v142, v122
	v_add_f32_e32 v143, v143, v123
	v_add_f32_e32 v140, v140, v116
	v_add_f32_e32 v141, v141, v117
	v_add_f32_e32 v142, v142, v118
	v_add_f32_e32 v143, v143, v119
	v_add_f32_e32 v140, v140, v112
	v_add_f32_e32 v141, v141, v113
	v_add_f32_e32 v142, v142, v114
	v_add_f32_e32 v143, v143, v115
	v_add_f32_e32 v140, v140, v108
	v_add_f32_e32 v141, v141, v109
	v_add_f32_e32 v142, v142, v110
	v_add_f32_e32 v143, v143, v111
	v_add_f32_e32 v140, v140, v104
	v_add_f32_e32 v141, v141, v105
	v_add_f32_e32 v142, v142, v106
	v_add_f32_e32 v143, v143, v107
	v_add_f32_e32 v140, v140, v100
	v_add_f32_e32 v141, v141, v101
	v_add_f32_e32 v142, v142, v102
	v_add_f32_e32 v143, v143, v103
	v_add_f32_e32 v140, v140, v96
	v_add_f32_e32 v141, v141, v97
	v_add_f32_e32 v142, v142, v98
	v_add_f32_e32 v143, v143, v99
	v_add_f32_e32 v140, v140, v92
	v_add_f32_e32 v141, v141, v93
	v_add_f32_e32 v142, v142, v94
	v_add_f32_e32 v143, v143, v95
	v_add_f32_e32 v140, v140, v88
	v_add_f32_e32 v141, v141, v89
	v_add_f32_e32 v142, v142, v90
	v_add_f32_e32 v143, v143, v91
	v_add_f32_e32 v140, v140, v84
	v_add_f32_e32 v141, v141, v85
	v_add_f32_e32 v142, v142, v86
	v_add_f32_e32 v143, v143, v87
	v_add_f32_e32 v140, v140, v80
	v_add_f32_e32 v141, v141, v81
	v_add_f32_e32 v142, v142, v82
	v_add_f32_e32 v143, v143, v83
	v_add_f32_e32 v140, v140, v76
	v_add_f32_e32 v141, v141, v77
	v_add_f32_e32 v142, v142, v78
	v_add_f32_e32 v143, v143, v79
	v_add_f32_e32 v140, v140, v72
	v_add_f32_e32 v141, v141, v73
	v_add_f32_e32 v142, v142, v74
	v_add_f32_e32 v143, v143, v75
	v_mul_f32_e32 v140, 0x3d800000, v140
	v_mul_f32_e32 v141, 0x3d800000, v141
	v_mul_f32_e32 v142, 0x3d800000, v142
	v_mul_f32_e32 v143, 0x3d800000, v143
	v_sub_f32_e32 v140, v140, v132
	v_sub_f32_e32 v141, v141, v133
	v_sub_f32_e32 v142, v142, v134
	v_sub_f32_e32 v143, v143, v135
	v_cvt_pk_bf16_f32 v144, v140, v141
	v_cvt_pk_bf16_f32 v145, v142, v143
	global_store_dwordx2 v11, v[144:145], s[24:25]
	s_add_u32 s24, s24, 0x800
	s_addc_u32 s25, s25, 0
	s_waitcnt vmcnt(0)
	v_and_b32_e32 v139, 0xffff0000, v137
	v_lshlrev_b32_e32 v138, 16, v137
	v_and_b32_e32 v137, 0xffff0000, v136
	v_lshlrev_b32_e32 v136, 16, v136
	v_add_f32_e32 v140, v136, v132
	v_add_f32_e32 v141, v137, v133
	v_add_f32_e32 v142, v138, v134
	v_add_f32_e32 v143, v139, v135
	v_add_f32_e32 v140, v140, v128
	v_add_f32_e32 v141, v141, v129
	v_add_f32_e32 v142, v142, v130
	v_add_f32_e32 v143, v143, v131
	v_add_f32_e32 v140, v140, v124
	v_add_f32_e32 v141, v141, v125
	v_add_f32_e32 v142, v142, v126
	v_add_f32_e32 v143, v143, v127
	v_add_f32_e32 v140, v140, v120
	v_add_f32_e32 v141, v141, v121
	v_add_f32_e32 v142, v142, v122
	v_add_f32_e32 v143, v143, v123
	v_add_f32_e32 v140, v140, v116
	v_add_f32_e32 v141, v141, v117
	v_add_f32_e32 v142, v142, v118
	v_add_f32_e32 v143, v143, v119
	v_add_f32_e32 v140, v140, v112
	v_add_f32_e32 v141, v141, v113
	v_add_f32_e32 v142, v142, v114
	v_add_f32_e32 v143, v143, v115
	v_add_f32_e32 v140, v140, v108
	v_add_f32_e32 v141, v141, v109
	v_add_f32_e32 v142, v142, v110
	v_add_f32_e32 v143, v143, v111
	v_add_f32_e32 v140, v140, v104
	v_add_f32_e32 v141, v141, v105
	v_add_f32_e32 v142, v142, v106
	v_add_f32_e32 v143, v143, v107
	v_add_f32_e32 v140, v140, v100
	v_add_f32_e32 v141, v141, v101
	v_add_f32_e32 v142, v142, v102
	v_add_f32_e32 v143, v143, v103
	v_add_f32_e32 v140, v140, v96
	v_add_f32_e32 v141, v141, v97
	v_add_f32_e32 v142, v142, v98
	v_add_f32_e32 v143, v143, v99
	v_add_f32_e32 v140, v140, v92
	v_add_f32_e32 v141, v141, v93
	v_add_f32_e32 v142, v142, v94
	v_add_f32_e32 v143, v143, v95
	v_add_f32_e32 v140, v140, v88
	v_add_f32_e32 v141, v141, v89
	v_add_f32_e32 v142, v142, v90
	v_add_f32_e32 v143, v143, v91
	v_add_f32_e32 v140, v140, v84
	v_add_f32_e32 v141, v141, v85
	v_add_f32_e32 v142, v142, v86
	v_add_f32_e32 v143, v143, v87
	v_add_f32_e32 v140, v140, v80
	v_add_f32_e32 v141, v141, v81
	v_add_f32_e32 v142, v142, v82
	v_add_f32_e32 v143, v143, v83
	v_add_f32_e32 v140, v140, v76
	v_add_f32_e32 v141, v141, v77
	v_add_f32_e32 v142, v142, v78
	v_add_f32_e32 v143, v143, v79
	v_mul_f32_e32 v140, 0x3d800000, v140
	v_mul_f32_e32 v141, 0x3d800000, v141
	v_mul_f32_e32 v142, 0x3d800000, v142
	v_mul_f32_e32 v143, 0x3d800000, v143
	v_sub_f32_e32 v140, v140, v136
	v_sub_f32_e32 v141, v141, v137
	v_sub_f32_e32 v142, v142, v138
	v_sub_f32_e32 v143, v143, v139
	v_cvt_pk_bf16_f32 v144, v140, v141
	v_cvt_pk_bf16_f32 v145, v142, v143
	global_store_dwordx2 v11, v[144:145], s[24:25]
	s_add_u32 s24, s24, 0x800
	s_addc_u32 s25, s25, 0
	s_cmp_eq_u32 s18, 126
	s_cbranch_scc0 .Lp13f_next3
	s_mul_i32 s26, s17, 61440
	s_add_u32 s26, s26, 0x431c000
	s_add_u32 s22, s12, s26
	s_addc_u32 s23, s13, 0
	global_store_dwordx4 v12, v[80:83], s[22:23]
	s_add_u32 s22, s22, 0x1000
	s_addc_u32 s23, s23, 0
	global_store_dwordx4 v12, v[84:87], s[22:23]
	s_add_u32 s22, s22, 0x1000
	s_addc_u32 s23, s23, 0
	global_store_dwordx4 v12, v[88:91], s[22:23]
	s_add_u32 s22, s22, 0x1000
	s_addc_u32 s23, s23, 0
	global_store_dwordx4 v12, v[92:95], s[22:23]
	s_add_u32 s22, s22, 0x1000
	s_addc_u32 s23, s23, 0
	global_store_dwordx4 v12, v[96:99], s[22:23]
	s_add_u32 s22, s22, 0x1000
	s_addc_u32 s23, s23, 0
	global_store_dwordx4 v12, v[100:103], s[22:23]
	s_add_u32 s22, s22, 0x1000
	s_addc_u32 s23, s23, 0
	global_store_dwordx4 v12, v[104:107], s[22:23]
	s_add_u32 s22, s22, 0x1000
	s_addc_u32 s23, s23, 0
	global_store_dwordx4 v12, v[108:111], s[22:23]
	s_add_u32 s22, s22, 0x1000
	s_addc_u32 s23, s23, 0
	global_store_dwordx4 v12, v[112:115], s[22:23]
	s_add_u32 s22, s22, 0x1000
	s_addc_u32 s23, s23, 0
	global_store_dwordx4 v12, v[116:119], s[22:23]
	s_add_u32 s22, s22, 0x1000
	s_addc_u32 s23, s23, 0
	global_store_dwordx4 v12, v[120:123], s[22:23]
	s_add_u32 s22, s22, 0x1000
	s_addc_u32 s23, s23, 0
	global_store_dwordx4 v12, v[124:127], s[22:23]
	s_add_u32 s22, s22, 0x1000
	s_addc_u32 s23, s23, 0
	global_store_dwordx4 v12, v[128:131], s[22:23]
	s_add_u32 s22, s22, 0x1000
	s_addc_u32 s23, s23, 0
	global_store_dwordx4 v12, v[132:135], s[22:23]
	s_add_u32 s22, s22, 0x1000
	s_addc_u32 s23, s23, 0
	global_store_dwordx4 v12, v[136:139], s[22:23]
	s_add_u32 s22, s22, 0x1000
	s_addc_u32 s23, s23, 0

.Lp13f_next:
	s_add_u32 s15, s15, s34
	s_branch .Lp13f_loop
.Lp13f_done:
	s_nop 0
	v_lshl_add_u32 v14, s46, 8, v196
	s_mov_b32 s0, 0x810000
	v_cmp_gt_i32_e32 vcc, s0, v14
	v_readlane_b32 s0, v254, 2
	v_readlane_b32 s1, v254, 3
	s_nop 0
	v_mov_b32_e32 v0, s0
	v_mov_b32_e32 v1, s1
	s_and_saveexec_b64 s[2:3], vcc
	s_cbranch_execz .LBB0_1313
	s_load_dwordx2 s[0:1], s[92:93], 0xf8
	s_waitcnt lgkmcnt(0)
	s_load_dwordx2 s[18:19], s[92:93], 0x28
	s_lshl_b32 s33, s34, 8
	s_load_dwordx4 s[20:23], s[92:93], 0x150
	s_movk_i32 s28, 0xf000
	s_add_u32 s24, s0, 0x8d54000
	s_addc_u32 s25, s1, 0
	s_add_u32 s26, s0, 0x431c000
	s_addc_u32 s27, s1, 0
	s_waitcnt lgkmcnt(0)
	s_add_u32 s30, s20, 0xfffff000
	v_lshlrev_b32_e32 v0, 1, v196
	s_mov_b32 s29, -1
	s_addc_u32 s31, s21, -1
	v_lshl_add_u32 v15, s46, 9, v0
	s_lshl_b32 s47, s34, 9
	s_mov_b64 s[36:37], 0
	s_movk_i32 s48, 0xff
	v_mov_b32_e32 v1, 0
	s_movk_i32 s49, 0x3fff
	s_movk_i32 s50, 0xc000
	s_mov_b32 s51, 0xf000
	s_movk_i32 s52, 0x2000
	s_movk_i32 s53, 0x4000
	s_movk_i32 s54, 0x6000
	s_mov_b32 s55, 0x8000
	s_mov_b32 s56, 0xa000
	s_mov_b32 s57, 0xb000
	s_mov_b32 s58, 0xc000
	s_mov_b32 s59, 0xd000
	s_movk_i32 s60, 0x7f0
	s_mov_b32 s61, 0x80ffff
	s_branch .LBB0_1252
.Lp13_skip:
	v_add_u32_e32 v14, s33, v14
	v_add_u32_e32 v15, s47, v15
	v_cmp_lt_i32_e32 vcc, s61, v14
	s_or_b64 s[36:37], vcc, s[36:37]
	s_andn2_b64 exec, exec, s[36:37]
	s_cbranch_execz .LBB0_1312
	s_branch .LBB0_1252

.LBB0_1252:
	v_readfirstlane_b32 s98, v14
	s_nop 3
	s_lshr_b32 s99, s98, 9
	s_cmp_ge_u32 s99, 0x4000
	s_cbranch_scc1 .Lp13_slow
	s_and_b32 s99, s99, 0x7ff
	s_cmp_ge_u32 s99, 16
	s_cbranch_scc1 .Lp13_skip
